# dprep LoRA matmuls (3x [16x64]x[64x256]) moved from VALU pk_fma loop to v_mfma_f32_16x16x4_f32 (f32 operands), LDS transpose in wave-private staging rows
# speedup vs baseline: 1.0214x; 1.0153x over previous
.LBB0_285:
	v_lshlrev_b64 v[30:31], 2, v[0:1]
	v_lshl_add_u64 v[34:35], s[4:5], 0, v[30:31]
	v_lshl_add_u64 v[36:37], s[6:7], 0, v[30:31]
	global_load_dword v23, v[34:35], off
	global_load_dword v19, v[34:35], off offset:1024
	global_load_dword v1, v[34:35], off offset:2048
	global_load_dword v115, v[36:37], off
	global_load_dword v114, v[36:37], off offset:1024
	global_load_dword v21, v[36:37], off offset:2048
	v_mov_b32_e32 v36, 0
	v_lshl_add_u64 v[108:109], s[8:9], 0, v[30:31]
	v_lshl_add_u64 v[110:111], s[10:11], 0, v[30:31]
	s_mov_b64 s[12:13], 0x1000
	v_and_b32_e32 v188, 63, v179
	v_and_b32_e32 v190, 15, v188
	v_lshrrev_b32_e32 v191, 4, v188
	v_lshlrev_b32_e32 v232, 4, v190
	v_lshl_add_u32 v232, v191, 10, v232
	v_lshlrev_b32_e32 v192, 2, v188
	v_sub_u32_e32 v232, v232, v192
	v_ashrrev_i32_e32 v233, 31, v232
	v_lshl_add_u64 v[108:109], v[108:109], 0, v[232:233]
	v_lshl_add_u64 v[110:111], v[110:111], 0, v[232:233]
	v_add_co_u32_e32 v112, vcc, 0x10000, v108
	s_nop 0
	v_addc_co_u32_e32 v113, vcc, 0, v109, vcc
	v_lshrrev_b32_e32 v192, 6, v179
	v_lshlrev_b32_e32 v192, 7, v192
	v_add_u32_e32 v192, 0x3010, v192
	v_lshl_add_u32 v184, v190, 10, v192
	v_lshl_add_u32 v184, v191, 4, v184
	v_lshrrev_b32_e32 v212, 1, v188
	v_lshl_add_u32 v186, v212, 9, v192
	v_and_b32_e32 v212, 1, v188
	v_lshl_add_u32 v186, v212, 6, v186
	v_lshl_add_u32 v176, v188, 2, 16
	global_load_dwordx4 v[148:151], v[108:109], off
	v_lshl_add_u64 v[108:109], v[108:109], 0, s[12:13]
	ds_read_b32 v131, v176 offset:0
	global_load_dwordx4 v[152:155], v[108:109], off
	v_lshl_add_u64 v[108:109], v[108:109], 0, s[12:13]
	ds_read_b32 v156, v176 offset:256
	global_load_dwordx4 v[166:169], v[108:109], off
	v_lshl_add_u64 v[108:109], v[108:109], 0, s[12:13]
	ds_read_b32 v157, v176 offset:512
	global_load_dwordx4 v[170:173], v[108:109], off
	v_lshl_add_u64 v[108:109], v[108:109], 0, s[12:13]
	ds_read_b32 v158, v176 offset:768
	global_load_dwordx4 v[180:183], v[108:109], off
	v_lshl_add_u64 v[108:109], v[108:109], 0, s[12:13]
	ds_read_b32 v160, v176 offset:1024
	global_load_dwordx4 v[238:241], v[108:109], off
	v_lshl_add_u64 v[108:109], v[108:109], 0, s[12:13]
	ds_read_b32 v161, v176 offset:1280
	global_load_dwordx4 v[242:245], v[108:109], off
	v_lshl_add_u64 v[108:109], v[108:109], 0, s[12:13]
	ds_read_b32 v162, v176 offset:1536
	global_load_dwordx4 v[246:249], v[108:109], off
	v_lshl_add_u64 v[108:109], v[108:109], 0, s[12:13]
	ds_read_b32 v164, v176 offset:1792
	s_waitcnt vmcnt(7)
	s_waitcnt lgkmcnt(7)
	v_mfma_f32_16x16x4_f32 v[132:135], v131, v148, 0
	v_mfma_f32_16x16x4_f32 v[136:139], v131, v149, 0
	v_mfma_f32_16x16x4_f32 v[140:143], v131, v150, 0
	v_mfma_f32_16x16x4_f32 v[144:147], v131, v151, 0
	s_waitcnt vmcnt(6)
	s_waitcnt lgkmcnt(6)
	v_mfma_f32_16x16x4_f32 v[132:135], v156, v152, v[132:135]
	v_mfma_f32_16x16x4_f32 v[136:139], v156, v153, v[136:139]
	v_mfma_f32_16x16x4_f32 v[140:143], v156, v154, v[140:143]
	v_mfma_f32_16x16x4_f32 v[144:147], v156, v155, v[144:147]
	s_waitcnt vmcnt(5)
	s_waitcnt lgkmcnt(5)
	v_mfma_f32_16x16x4_f32 v[132:135], v157, v166, v[132:135]
	v_mfma_f32_16x16x4_f32 v[136:139], v157, v167, v[136:139]
	v_mfma_f32_16x16x4_f32 v[140:143], v157, v168, v[140:143]
	v_mfma_f32_16x16x4_f32 v[144:147], v157, v169, v[144:147]
	s_waitcnt vmcnt(4)
	s_waitcnt lgkmcnt(4)
	v_mfma_f32_16x16x4_f32 v[132:135], v158, v170, v[132:135]
	v_mfma_f32_16x16x4_f32 v[136:139], v158, v171, v[136:139]
	v_mfma_f32_16x16x4_f32 v[140:143], v158, v172, v[140:143]
	v_mfma_f32_16x16x4_f32 v[144:147], v158, v173, v[144:147]
	global_load_dwordx4 v[148:151], v[108:109], off
	v_lshl_add_u64 v[108:109], v[108:109], 0, s[12:13]
	ds_read_b32 v131, v176 offset:2048
	global_load_dwordx4 v[152:155], v[108:109], off
	v_lshl_add_u64 v[108:109], v[108:109], 0, s[12:13]
	ds_read_b32 v156, v176 offset:2304
	global_load_dwordx4 v[166:169], v[108:109], off
	v_lshl_add_u64 v[108:109], v[108:109], 0, s[12:13]
	ds_read_b32 v157, v176 offset:2560
	global_load_dwordx4 v[170:173], v[108:109], off
	v_lshl_add_u64 v[108:109], v[108:109], 0, s[12:13]
	ds_read_b32 v158, v176 offset:2816
	s_waitcnt vmcnt(7)
	s_waitcnt lgkmcnt(7)
	v_mfma_f32_16x16x4_f32 v[132:135], v160, v180, v[132:135]
	v_mfma_f32_16x16x4_f32 v[136:139], v160, v181, v[136:139]
	v_mfma_f32_16x16x4_f32 v[140:143], v160, v182, v[140:143]
	v_mfma_f32_16x16x4_f32 v[144:147], v160, v183, v[144:147]
	s_waitcnt vmcnt(6)
	s_waitcnt lgkmcnt(6)
	v_mfma_f32_16x16x4_f32 v[132:135], v161, v238, v[132:135]
	v_mfma_f32_16x16x4_f32 v[136:139], v161, v239, v[136:139]
	v_mfma_f32_16x16x4_f32 v[140:143], v161, v240, v[140:143]
	v_mfma_f32_16x16x4_f32 v[144:147], v161, v241, v[144:147]
	s_waitcnt vmcnt(5)
	s_waitcnt lgkmcnt(5)
	v_mfma_f32_16x16x4_f32 v[132:135], v162, v242, v[132:135]
	v_mfma_f32_16x16x4_f32 v[136:139], v162, v243, v[136:139]
	v_mfma_f32_16x16x4_f32 v[140:143], v162, v244, v[140:143]
	v_mfma_f32_16x16x4_f32 v[144:147], v162, v245, v[144:147]
	s_waitcnt vmcnt(4)
	s_waitcnt lgkmcnt(4)
	v_mfma_f32_16x16x4_f32 v[132:135], v164, v246, v[132:135]
	v_mfma_f32_16x16x4_f32 v[136:139], v164, v247, v[136:139]
	v_mfma_f32_16x16x4_f32 v[140:143], v164, v248, v[140:143]
	v_mfma_f32_16x16x4_f32 v[144:147], v164, v249, v[144:147]
	global_load_dwordx4 v[180:183], v[108:109], off
	v_lshl_add_u64 v[108:109], v[108:109], 0, s[12:13]
	ds_read_b32 v160, v176 offset:3072
	global_load_dwordx4 v[238:241], v[108:109], off
	v_lshl_add_u64 v[108:109], v[108:109], 0, s[12:13]
	ds_read_b32 v161, v176 offset:3328
	global_load_dwordx4 v[242:245], v[108:109], off
	v_lshl_add_u64 v[108:109], v[108:109], 0, s[12:13]
	ds_read_b32 v162, v176 offset:3584
	global_load_dwordx4 v[246:249], v[108:109], off
	v_lshl_add_u64 v[108:109], v[108:109], 0, s[12:13]
	ds_read_b32 v164, v176 offset:3840
	s_waitcnt vmcnt(7)
	s_waitcnt lgkmcnt(7)
	v_mfma_f32_16x16x4_f32 v[132:135], v131, v148, v[132:135]
	v_mfma_f32_16x16x4_f32 v[136:139], v131, v149, v[136:139]
	v_mfma_f32_16x16x4_f32 v[140:143], v131, v150, v[140:143]
	v_mfma_f32_16x16x4_f32 v[144:147], v131, v151, v[144:147]
	s_waitcnt vmcnt(6)
	s_waitcnt lgkmcnt(6)
	v_mfma_f32_16x16x4_f32 v[132:135], v156, v152, v[132:135]
	v_mfma_f32_16x16x4_f32 v[136:139], v156, v153, v[136:139]
	v_mfma_f32_16x16x4_f32 v[140:143], v156, v154, v[140:143]
	v_mfma_f32_16x16x4_f32 v[144:147], v156, v155, v[144:147]
	s_waitcnt vmcnt(5)
	s_waitcnt lgkmcnt(5)
	v_mfma_f32_16x16x4_f32 v[132:135], v157, v166, v[132:135]
	v_mfma_f32_16x16x4_f32 v[136:139], v157, v167, v[136:139]
	v_mfma_f32_16x16x4_f32 v[140:143], v157, v168, v[140:143]
	v_mfma_f32_16x16x4_f32 v[144:147], v157, v169, v[144:147]
	s_waitcnt vmcnt(4)
	s_waitcnt lgkmcnt(4)
	v_mfma_f32_16x16x4_f32 v[132:135], v158, v170, v[132:135]
	v_mfma_f32_16x16x4_f32 v[136:139], v158, v171, v[136:139]
	v_mfma_f32_16x16x4_f32 v[140:143], v158, v172, v[140:143]
	v_mfma_f32_16x16x4_f32 v[144:147], v158, v173, v[144:147]
	global_load_dwordx4 v[148:151], v[112:113], off
	v_lshl_add_u64 v[112:113], v[112:113], 0, s[12:13]
	ds_read_b32 v131, v176 offset:4096
	global_load_dwordx4 v[152:155], v[112:113], off
	v_lshl_add_u64 v[112:113], v[112:113], 0, s[12:13]
	ds_read_b32 v156, v176 offset:4352
	global_load_dwordx4 v[166:169], v[112:113], off
	v_lshl_add_u64 v[112:113], v[112:113], 0, s[12:13]
	ds_read_b32 v157, v176 offset:4608
	global_load_dwordx4 v[170:173], v[112:113], off
	v_lshl_add_u64 v[112:113], v[112:113], 0, s[12:13]
	ds_read_b32 v158, v176 offset:4864
	s_waitcnt vmcnt(7)
	s_waitcnt lgkmcnt(7)
	v_mfma_f32_16x16x4_f32 v[132:135], v160, v180, v[132:135]
	v_mfma_f32_16x16x4_f32 v[136:139], v160, v181, v[136:139]
	v_mfma_f32_16x16x4_f32 v[140:143], v160, v182, v[140:143]
	v_mfma_f32_16x16x4_f32 v[144:147], v160, v183, v[144:147]
	s_waitcnt vmcnt(6)
	s_waitcnt lgkmcnt(6)
	v_mfma_f32_16x16x4_f32 v[132:135], v161, v238, v[132:135]
	v_mfma_f32_16x16x4_f32 v[136:139], v161, v239, v[136:139]
	v_mfma_f32_16x16x4_f32 v[140:143], v161, v240, v[140:143]
	v_mfma_f32_16x16x4_f32 v[144:147], v161, v241, v[144:147]
	s_waitcnt vmcnt(5)
	s_waitcnt lgkmcnt(5)
	v_mfma_f32_16x16x4_f32 v[132:135], v162, v242, v[132:135]
	v_mfma_f32_16x16x4_f32 v[136:139], v162, v243, v[136:139]
	v_mfma_f32_16x16x4_f32 v[140:143], v162, v244, v[140:143]
	v_mfma_f32_16x16x4_f32 v[144:147], v162, v245, v[144:147]
	s_waitcnt vmcnt(4)
	s_waitcnt lgkmcnt(4)
	v_mfma_f32_16x16x4_f32 v[132:135], v164, v246, v[132:135]
	v_mfma_f32_16x16x4_f32 v[136:139], v164, v247, v[136:139]
	v_mfma_f32_16x16x4_f32 v[140:143], v164, v248, v[140:143]
	v_mfma_f32_16x16x4_f32 v[144:147], v164, v249, v[144:147]
	s_nop 15
	ds_write_b128 v184, v[132:135] offset:0
	ds_write_b128 v184, v[136:139] offset:64
	ds_write_b128 v184, v[140:143] offset:512
	ds_write_b128 v184, v[144:147] offset:576
	global_load_dwordx4 v[180:183], v[112:113], off
	v_lshl_add_u64 v[112:113], v[112:113], 0, s[12:13]
	ds_read_b32 v160, v176 offset:5120
	global_load_dwordx4 v[238:241], v[112:113], off
	v_lshl_add_u64 v[112:113], v[112:113], 0, s[12:13]
	ds_read_b32 v161, v176 offset:5376
	global_load_dwordx4 v[242:245], v[112:113], off
	v_lshl_add_u64 v[112:113], v[112:113], 0, s[12:13]
	ds_read_b32 v162, v176 offset:5632
	global_load_dwordx4 v[246:249], v[112:113], off
	v_lshl_add_u64 v[112:113], v[112:113], 0, s[12:13]
	ds_read_b32 v164, v176 offset:5888
	s_waitcnt vmcnt(7)
	s_waitcnt lgkmcnt(11)
	v_mfma_f32_16x16x4_f32 v[132:135], v131, v148, 0
	v_mfma_f32_16x16x4_f32 v[136:139], v131, v149, 0
	v_mfma_f32_16x16x4_f32 v[140:143], v131, v150, 0
	v_mfma_f32_16x16x4_f32 v[144:147], v131, v151, 0
	s_waitcnt vmcnt(6)
	s_waitcnt lgkmcnt(10)
	v_mfma_f32_16x16x4_f32 v[132:135], v156, v152, v[132:135]
	v_mfma_f32_16x16x4_f32 v[136:139], v156, v153, v[136:139]
	v_mfma_f32_16x16x4_f32 v[140:143], v156, v154, v[140:143]
	v_mfma_f32_16x16x4_f32 v[144:147], v156, v155, v[144:147]
	s_waitcnt vmcnt(5)
	s_waitcnt lgkmcnt(9)
	v_mfma_f32_16x16x4_f32 v[132:135], v157, v166, v[132:135]
	v_mfma_f32_16x16x4_f32 v[136:139], v157, v167, v[136:139]
	v_mfma_f32_16x16x4_f32 v[140:143], v157, v168, v[140:143]
	v_mfma_f32_16x16x4_f32 v[144:147], v157, v169, v[144:147]
	s_waitcnt vmcnt(4)
	s_waitcnt lgkmcnt(8)
	v_mfma_f32_16x16x4_f32 v[132:135], v158, v170, v[132:135]
	v_mfma_f32_16x16x4_f32 v[136:139], v158, v171, v[136:139]
	v_mfma_f32_16x16x4_f32 v[140:143], v158, v172, v[140:143]
	v_mfma_f32_16x16x4_f32 v[144:147], v158, v173, v[144:147]
	global_load_dwordx4 v[148:151], v[112:113], off
	v_lshl_add_u64 v[112:113], v[112:113], 0, s[12:13]
	ds_read_b32 v131, v176 offset:6144
	global_load_dwordx4 v[152:155], v[112:113], off
	v_lshl_add_u64 v[112:113], v[112:113], 0, s[12:13]
	ds_read_b32 v156, v176 offset:6400
	global_load_dwordx4 v[166:169], v[112:113], off
	v_lshl_add_u64 v[112:113], v[112:113], 0, s[12:13]
	ds_read_b32 v157, v176 offset:6656
	global_load_dwordx4 v[170:173], v[112:113], off
	v_lshl_add_u64 v[112:113], v[112:113], 0, s[12:13]
	ds_read_b32 v158, v176 offset:6912
	s_waitcnt vmcnt(7)
	s_waitcnt lgkmcnt(7)
	ds_read_b64 v[106:107], v186 offset:0
	ds_read_b64 v[98:99], v186 offset:8
	ds_read_b64 v[88:89], v186 offset:16
	ds_read_b64 v[78:79], v186 offset:24
	ds_read_b64 v[68:69], v186 offset:32
	ds_read_b64 v[56:57], v186 offset:40
	ds_read_b64 v[46:47], v186 offset:48
	ds_read_b64 v[36:37], v186 offset:56
	v_mfma_f32_16x16x4_f32 v[132:135], v160, v180, v[132:135]
	v_mfma_f32_16x16x4_f32 v[136:139], v160, v181, v[136:139]
	v_mfma_f32_16x16x4_f32 v[140:143], v160, v182, v[140:143]
	v_mfma_f32_16x16x4_f32 v[144:147], v160, v183, v[144:147]
	s_waitcnt vmcnt(6)
	s_waitcnt lgkmcnt(14)
	v_mfma_f32_16x16x4_f32 v[132:135], v161, v238, v[132:135]
	v_mfma_f32_16x16x4_f32 v[136:139], v161, v239, v[136:139]
	v_mfma_f32_16x16x4_f32 v[140:143], v161, v240, v[140:143]
	v_mfma_f32_16x16x4_f32 v[144:147], v161, v241, v[144:147]
	s_waitcnt vmcnt(5)
	s_waitcnt lgkmcnt(13)
	v_mfma_f32_16x16x4_f32 v[132:135], v162, v242, v[132:135]
	v_mfma_f32_16x16x4_f32 v[136:139], v162, v243, v[136:139]
	v_mfma_f32_16x16x4_f32 v[140:143], v162, v244, v[140:143]
	v_mfma_f32_16x16x4_f32 v[144:147], v162, v245, v[144:147]
	s_waitcnt vmcnt(4)
	s_waitcnt lgkmcnt(12)
	v_mfma_f32_16x16x4_f32 v[132:135], v164, v246, v[132:135]
	v_mfma_f32_16x16x4_f32 v[136:139], v164, v247, v[136:139]
	v_mfma_f32_16x16x4_f32 v[140:143], v164, v248, v[140:143]
	v_mfma_f32_16x16x4_f32 v[144:147], v164, v249, v[144:147]
	global_load_dwordx4 v[180:183], v[112:113], off
	v_lshl_add_u64 v[112:113], v[112:113], 0, s[12:13]
	ds_read_b32 v160, v176 offset:7168
	global_load_dwordx4 v[238:241], v[112:113], off
	v_lshl_add_u64 v[112:113], v[112:113], 0, s[12:13]
	ds_read_b32 v161, v176 offset:7424
	global_load_dwordx4 v[242:245], v[112:113], off
	v_lshl_add_u64 v[112:113], v[112:113], 0, s[12:13]
	ds_read_b32 v162, v176 offset:7680
	global_load_dwordx4 v[246:249], v[112:113], off
	v_lshl_add_u64 v[112:113], v[112:113], 0, s[12:13]
	ds_read_b32 v164, v176 offset:7936
	s_waitcnt vmcnt(7)
	s_waitcnt lgkmcnt(15)
	v_mfma_f32_16x16x4_f32 v[132:135], v131, v148, v[132:135]
	v_mfma_f32_16x16x4_f32 v[136:139], v131, v149, v[136:139]
	v_mfma_f32_16x16x4_f32 v[140:143], v131, v150, v[140:143]
	v_mfma_f32_16x16x4_f32 v[144:147], v131, v151, v[144:147]
	s_waitcnt vmcnt(6)
	s_waitcnt lgkmcnt(14)
	v_mfma_f32_16x16x4_f32 v[132:135], v156, v152, v[132:135]
	v_mfma_f32_16x16x4_f32 v[136:139], v156, v153, v[136:139]
	v_mfma_f32_16x16x4_f32 v[140:143], v156, v154, v[140:143]
	v_mfma_f32_16x16x4_f32 v[144:147], v156, v155, v[144:147]
	s_waitcnt vmcnt(5)
	s_waitcnt lgkmcnt(13)
	v_mfma_f32_16x16x4_f32 v[132:135], v157, v166, v[132:135]
	v_mfma_f32_16x16x4_f32 v[136:139], v157, v167, v[136:139]
	v_mfma_f32_16x16x4_f32 v[140:143], v157, v168, v[140:143]
	v_mfma_f32_16x16x4_f32 v[144:147], v157, v169, v[144:147]
	s_waitcnt vmcnt(4)
	s_waitcnt lgkmcnt(12)
	v_mfma_f32_16x16x4_f32 v[132:135], v158, v170, v[132:135]
	v_mfma_f32_16x16x4_f32 v[136:139], v158, v171, v[136:139]
	v_mfma_f32_16x16x4_f32 v[140:143], v158, v172, v[140:143]
	v_mfma_f32_16x16x4_f32 v[144:147], v158, v173, v[144:147]
	global_load_dwordx4 v[148:151], v[110:111], off
	v_lshl_add_u64 v[110:111], v[110:111], 0, s[12:13]
	ds_read_b32 v131, v176 offset:8192
	global_load_dwordx4 v[152:155], v[110:111], off
	v_lshl_add_u64 v[110:111], v[110:111], 0, s[12:13]
	ds_read_b32 v156, v176 offset:8448
	global_load_dwordx4 v[166:169], v[110:111], off
	v_lshl_add_u64 v[110:111], v[110:111], 0, s[12:13]
	ds_read_b32 v157, v176 offset:8704
	global_load_dwordx4 v[170:173], v[110:111], off
	v_lshl_add_u64 v[110:111], v[110:111], 0, s[12:13]
	ds_read_b32 v158, v176 offset:8960
	s_waitcnt vmcnt(7)
	s_waitcnt lgkmcnt(7)
	v_mfma_f32_16x16x4_f32 v[132:135], v160, v180, v[132:135]
	v_mfma_f32_16x16x4_f32 v[136:139], v160, v181, v[136:139]
	v_mfma_f32_16x16x4_f32 v[140:143], v160, v182, v[140:143]
	v_mfma_f32_16x16x4_f32 v[144:147], v160, v183, v[144:147]
	s_waitcnt vmcnt(6)
	s_waitcnt lgkmcnt(6)
	v_mfma_f32_16x16x4_f32 v[132:135], v161, v238, v[132:135]
	v_mfma_f32_16x16x4_f32 v[136:139], v161, v239, v[136:139]
	v_mfma_f32_16x16x4_f32 v[140:143], v161, v240, v[140:143]
	v_mfma_f32_16x16x4_f32 v[144:147], v161, v241, v[144:147]
	s_waitcnt vmcnt(5)
	s_waitcnt lgkmcnt(5)
	v_mfma_f32_16x16x4_f32 v[132:135], v162, v242, v[132:135]
	v_mfma_f32_16x16x4_f32 v[136:139], v162, v243, v[136:139]
	v_mfma_f32_16x16x4_f32 v[140:143], v162, v244, v[140:143]
	v_mfma_f32_16x16x4_f32 v[144:147], v162, v245, v[144:147]
	s_waitcnt vmcnt(4)
	s_waitcnt lgkmcnt(4)
	v_mfma_f32_16x16x4_f32 v[132:135], v164, v246, v[132:135]
	v_mfma_f32_16x16x4_f32 v[136:139], v164, v247, v[136:139]
	v_mfma_f32_16x16x4_f32 v[140:143], v164, v248, v[140:143]
	v_mfma_f32_16x16x4_f32 v[144:147], v164, v249, v[144:147]
	s_nop 15
	ds_write_b128 v184, v[132:135] offset:16384
	ds_write_b128 v184, v[136:139] offset:16448
	ds_write_b128 v184, v[140:143] offset:16896
	ds_write_b128 v184, v[144:147] offset:16960
	global_load_dwordx4 v[180:183], v[110:111], off
	v_lshl_add_u64 v[110:111], v[110:111], 0, s[12:13]
	ds_read_b32 v160, v176 offset:9216
	global_load_dwordx4 v[238:241], v[110:111], off
	v_lshl_add_u64 v[110:111], v[110:111], 0, s[12:13]
	ds_read_b32 v161, v176 offset:9472
	global_load_dwordx4 v[242:245], v[110:111], off
	v_lshl_add_u64 v[110:111], v[110:111], 0, s[12:13]
	ds_read_b32 v162, v176 offset:9728
	global_load_dwordx4 v[246:249], v[110:111], off
	v_lshl_add_u64 v[110:111], v[110:111], 0, s[12:13]
	ds_read_b32 v164, v176 offset:9984
	s_waitcnt vmcnt(7)
	s_waitcnt lgkmcnt(11)
	v_mfma_f32_16x16x4_f32 v[132:135], v131, v148, 0
	v_mfma_f32_16x16x4_f32 v[136:139], v131, v149, 0
	v_mfma_f32_16x16x4_f32 v[140:143], v131, v150, 0
	v_mfma_f32_16x16x4_f32 v[144:147], v131, v151, 0
	s_waitcnt vmcnt(6)
	s_waitcnt lgkmcnt(10)
	v_mfma_f32_16x16x4_f32 v[132:135], v156, v152, v[132:135]
	v_mfma_f32_16x16x4_f32 v[136:139], v156, v153, v[136:139]
	v_mfma_f32_16x16x4_f32 v[140:143], v156, v154, v[140:143]
	v_mfma_f32_16x16x4_f32 v[144:147], v156, v155, v[144:147]
	s_waitcnt vmcnt(5)
	s_waitcnt lgkmcnt(9)
	v_mfma_f32_16x16x4_f32 v[132:135], v157, v166, v[132:135]
	v_mfma_f32_16x16x4_f32 v[136:139], v157, v167, v[136:139]
	v_mfma_f32_16x16x4_f32 v[140:143], v157, v168, v[140:143]
	v_mfma_f32_16x16x4_f32 v[144:147], v157, v169, v[144:147]
	s_waitcnt vmcnt(4)
	s_waitcnt lgkmcnt(8)
	v_mfma_f32_16x16x4_f32 v[132:135], v158, v170, v[132:135]
	v_mfma_f32_16x16x4_f32 v[136:139], v158, v171, v[136:139]
	v_mfma_f32_16x16x4_f32 v[140:143], v158, v172, v[140:143]
	v_mfma_f32_16x16x4_f32 v[144:147], v158, v173, v[144:147]
	global_load_dwordx4 v[148:151], v[110:111], off
	v_lshl_add_u64 v[110:111], v[110:111], 0, s[12:13]
	ds_read_b32 v131, v176 offset:10240
	global_load_dwordx4 v[152:155], v[110:111], off
	v_lshl_add_u64 v[110:111], v[110:111], 0, s[12:13]
	ds_read_b32 v156, v176 offset:10496
	global_load_dwordx4 v[166:169], v[110:111], off
	v_lshl_add_u64 v[110:111], v[110:111], 0, s[12:13]
	ds_read_b32 v157, v176 offset:10752
	global_load_dwordx4 v[170:173], v[110:111], off
	v_lshl_add_u64 v[110:111], v[110:111], 0, s[12:13]
	ds_read_b32 v158, v176 offset:11008
	s_waitcnt vmcnt(7)
	s_waitcnt lgkmcnt(7)
	ds_read_b64 v[104:105], v186 offset:16384
	ds_read_b64 v[96:97], v186 offset:16392
	ds_read_b64 v[86:87], v186 offset:16400
	ds_read_b64 v[76:77], v186 offset:16408
	ds_read_b64 v[64:65], v186 offset:16416
	ds_read_b64 v[54:55], v186 offset:16424
	ds_read_b64 v[44:45], v186 offset:16432
	ds_read_b64 v[34:35], v186 offset:16440
	v_mfma_f32_16x16x4_f32 v[132:135], v160, v180, v[132:135]
	v_mfma_f32_16x16x4_f32 v[136:139], v160, v181, v[136:139]
	v_mfma_f32_16x16x4_f32 v[140:143], v160, v182, v[140:143]
	v_mfma_f32_16x16x4_f32 v[144:147], v160, v183, v[144:147]
	s_waitcnt vmcnt(6)
	s_waitcnt lgkmcnt(14)
	v_mfma_f32_16x16x4_f32 v[132:135], v161, v238, v[132:135]
	v_mfma_f32_16x16x4_f32 v[136:139], v161, v239, v[136:139]
	v_mfma_f32_16x16x4_f32 v[140:143], v161, v240, v[140:143]
	v_mfma_f32_16x16x4_f32 v[144:147], v161, v241, v[144:147]
	s_waitcnt vmcnt(5)
	s_waitcnt lgkmcnt(13)
	v_mfma_f32_16x16x4_f32 v[132:135], v162, v242, v[132:135]
	v_mfma_f32_16x16x4_f32 v[136:139], v162, v243, v[136:139]
	v_mfma_f32_16x16x4_f32 v[140:143], v162, v244, v[140:143]
	v_mfma_f32_16x16x4_f32 v[144:147], v162, v245, v[144:147]
	s_waitcnt vmcnt(4)
	s_waitcnt lgkmcnt(12)
	v_mfma_f32_16x16x4_f32 v[132:135], v164, v246, v[132:135]
	v_mfma_f32_16x16x4_f32 v[136:139], v164, v247, v[136:139]
	v_mfma_f32_16x16x4_f32 v[140:143], v164, v248, v[140:143]
	v_mfma_f32_16x16x4_f32 v[144:147], v164, v249, v[144:147]
	global_load_dwordx4 v[180:183], v[110:111], off
	v_lshl_add_u64 v[110:111], v[110:111], 0, s[12:13]
	ds_read_b32 v160, v176 offset:11264
	global_load_dwordx4 v[238:241], v[110:111], off
	v_lshl_add_u64 v[110:111], v[110:111], 0, s[12:13]
	ds_read_b32 v161, v176 offset:11520
	global_load_dwordx4 v[242:245], v[110:111], off
	v_lshl_add_u64 v[110:111], v[110:111], 0, s[12:13]
	ds_read_b32 v162, v176 offset:11776
	global_load_dwordx4 v[246:249], v[110:111], off
	v_lshl_add_u64 v[110:111], v[110:111], 0, s[12:13]
	ds_read_b32 v164, v176 offset:12032
	s_waitcnt vmcnt(7)
	s_waitcnt lgkmcnt(15)
	v_mfma_f32_16x16x4_f32 v[132:135], v131, v148, v[132:135]
	v_mfma_f32_16x16x4_f32 v[136:139], v131, v149, v[136:139]
	v_mfma_f32_16x16x4_f32 v[140:143], v131, v150, v[140:143]
	v_mfma_f32_16x16x4_f32 v[144:147], v131, v151, v[144:147]
	s_waitcnt vmcnt(6)
	s_waitcnt lgkmcnt(14)
	v_mfma_f32_16x16x4_f32 v[132:135], v156, v152, v[132:135]
	v_mfma_f32_16x16x4_f32 v[136:139], v156, v153, v[136:139]
	v_mfma_f32_16x16x4_f32 v[140:143], v156, v154, v[140:143]
	v_mfma_f32_16x16x4_f32 v[144:147], v156, v155, v[144:147]
	s_waitcnt vmcnt(5)
	s_waitcnt lgkmcnt(13)
	v_mfma_f32_16x16x4_f32 v[132:135], v157, v166, v[132:135]
	v_mfma_f32_16x16x4_f32 v[136:139], v157, v167, v[136:139]
	v_mfma_f32_16x16x4_f32 v[140:143], v157, v168, v[140:143]
	v_mfma_f32_16x16x4_f32 v[144:147], v157, v169, v[144:147]
	s_waitcnt vmcnt(4)
	s_waitcnt lgkmcnt(12)
	v_mfma_f32_16x16x4_f32 v[132:135], v158, v170, v[132:135]
	v_mfma_f32_16x16x4_f32 v[136:139], v158, v171, v[136:139]
	v_mfma_f32_16x16x4_f32 v[140:143], v158, v172, v[140:143]
	v_mfma_f32_16x16x4_f32 v[144:147], v158, v173, v[144:147]
	s_waitcnt vmcnt(3)
	s_waitcnt lgkmcnt(3)
	v_mfma_f32_16x16x4_f32 v[132:135], v160, v180, v[132:135]
	v_mfma_f32_16x16x4_f32 v[136:139], v160, v181, v[136:139]
	v_mfma_f32_16x16x4_f32 v[140:143], v160, v182, v[140:143]
	v_mfma_f32_16x16x4_f32 v[144:147], v160, v183, v[144:147]
	s_waitcnt vmcnt(2)
	s_waitcnt lgkmcnt(2)
	v_mfma_f32_16x16x4_f32 v[132:135], v161, v238, v[132:135]
	v_mfma_f32_16x16x4_f32 v[136:139], v161, v239, v[136:139]
	v_mfma_f32_16x16x4_f32 v[140:143], v161, v240, v[140:143]
	v_mfma_f32_16x16x4_f32 v[144:147], v161, v241, v[144:147]
	s_waitcnt vmcnt(1)
	s_waitcnt lgkmcnt(1)
	v_mfma_f32_16x16x4_f32 v[132:135], v162, v242, v[132:135]
	v_mfma_f32_16x16x4_f32 v[136:139], v162, v243, v[136:139]
	v_mfma_f32_16x16x4_f32 v[140:143], v162, v244, v[140:143]
	v_mfma_f32_16x16x4_f32 v[144:147], v162, v245, v[144:147]
	s_waitcnt vmcnt(0)
	s_waitcnt lgkmcnt(0)
	v_mfma_f32_16x16x4_f32 v[132:135], v164, v246, v[132:135]
	v_mfma_f32_16x16x4_f32 v[136:139], v164, v247, v[136:139]
	v_mfma_f32_16x16x4_f32 v[140:143], v164, v248, v[140:143]
	v_mfma_f32_16x16x4_f32 v[144:147], v164, v249, v[144:147]
	s_nop 15
	ds_write_b128 v184, v[132:135] offset:32768
	ds_write_b128 v184, v[136:139] offset:32832
	ds_write_b128 v184, v[140:143] offset:33280
	ds_write_b128 v184, v[144:147] offset:33344
	s_waitcnt vmcnt(0) lgkmcnt(0)
	ds_read_b64 v[102:103], v186 offset:32768
	ds_read_b64 v[94:95], v186 offset:32776
	ds_read_b64 v[84:85], v186 offset:32784
	ds_read_b64 v[72:73], v186 offset:32792
	ds_read_b64 v[62:63], v186 offset:32800
	ds_read_b64 v[52:53], v186 offset:32808
	ds_read_b64 v[42:43], v186 offset:32816
	ds_read_b64 v[30:31], v186 offset:32824
	s_waitcnt lgkmcnt(0)
	v_add_f32_e32 v106, v11, v106
	v_mul_f32_e32 v106, 0xbfb8aa3b, v106
	v_exp_f32_e32 v106, v106
	v_pk_add_f32 v[100:101], v[100:101], v[92:93] neg_lo:[0,1] neg_hi:[0,1]
	v_mov_b32_e32 v112, v93
	v_fmac_f32_e32 v112, v101, v23
	v_mov_b32_e32 v101, v92
	v_pk_add_f32 v[110:111], v[90:91], v[92:93] neg_lo:[0,1] neg_hi:[0,1]
	v_fmac_f32_e32 v101, v100, v19
	v_sub_f32_e32 v100, v130, v129
	v_fmac_f32_e32 v101, v110, v114
	v_fma_f32 v100, v100, v1, v129
	v_sub_f32_e32 v110, v128, v129
	v_add_f32_e32 v106, 1.0, v106
	v_fmac_f32_e32 v100, v110, v21
	v_div_scale_f32 v110, s[12:13], v106, v106, s39
	v_fmac_f32_e32 v112, v111, v115
	v_rcp_f32_e32 v111, v110
	v_add_f32_e32 v104, v9, v104
	v_mul_f32_e32 v104, 0xbfb8aa3b, v104
	v_exp_f32_e32 v104, v104
	v_fma_f32 v113, -v110, v111, 1.0
	v_fmac_f32_e32 v111, v113, v111
	v_div_scale_f32 v113, vcc, s39, v106, s39
	v_mul_f32_e32 v130, v113, v111
	v_fma_f32 v131, -v110, v130, v113
	v_fmac_f32_e32 v130, v131, v111
	v_fma_f32 v110, -v110, v130, v113
	v_div_fmas_f32 v110, v110, v111, v130
	v_add_f32_e32 v104, 1.0, v104
	v_div_fixup_f32 v106, v110, v106, s39
	v_div_scale_f32 v110, s[12:13], v104, v104, s39
	v_rcp_f32_e32 v111, v110
	v_add_f32_e32 v102, v7, v102
	v_mul_f32_e32 v102, 0xbfb8aa3b, v102
	v_exp_f32_e32 v102, v102
	v_fma_f32 v113, -v110, v111, 1.0
	v_fmac_f32_e32 v111, v113, v111
	v_div_scale_f32 v113, vcc, s39, v104, s39
	v_mul_f32_e32 v130, v113, v111
	v_fma_f32 v131, -v110, v130, v113
	v_fmac_f32_e32 v130, v131, v111
	v_fma_f32 v110, -v110, v130, v113
	v_div_fmas_f32 v110, v110, v111, v130
	v_add_f32_e32 v102, 1.0, v102
	v_div_fixup_f32 v104, v110, v104, s39
	v_div_scale_f32 v110, s[12:13], v102, v102, 1.0
	v_rcp_f32_e32 v111, v110
	v_mul_f32_e32 v106, 0x3fb8aa3b, v106
	v_exp_f32_e32 v106, v106
	v_mul_f32_e32 v104, 0x3fb8aa3b, v104
	v_fma_f32 v113, -v110, v111, 1.0
	v_fmac_f32_e32 v111, v113, v111
	v_div_scale_f32 v113, vcc, 1.0, v102, 1.0
	v_mul_f32_e32 v130, v113, v111
	v_fma_f32 v131, -v110, v130, v113
	v_fmac_f32_e32 v130, v131, v111
	v_fma_f32 v110, -v110, v130, v113
	v_div_fmas_f32 v110, v110, v111, v130
	v_div_fixup_f32 v102, v110, v102, 1.0
	v_mul_f32_e32 v110, v5, v101
	v_mul_f32_e32 v111, v110, v110
	v_exp_f32_e32 v104, v104
	v_lshl_add_u32 v109, v0, 1, 16
	v_mov_b32_dpp v111, v111 quad_perm:[1,0,3,2] row_mask:0xf bank_mask:0xf bound_ctrl:1
	v_fmac_f32_e32 v111, v110, v110
	v_cvt_pk_bf16_f32 v100, v100, s0
	ds_write_b16 v109, v100 offset:28672
	v_add_f32_dpp v111, v111, v111 quad_perm:[2,3,0,1] row_mask:0xf bank_mask:0xf bound_ctrl:1
	v_sub_f32_e32 v106, 1.0, v106
	v_sub_f32_e32 v104, 1.0, v104
	v_add_f32_dpp v111, v111, v111 row_half_mirror row_mask:0xf bank_mask:0xf bound_ctrl:1
	v_pk_add_f32 v[92:93], v[92:93], v[90:91] neg_lo:[0,1] neg_hi:[0,1]
	v_add_f32_e32 v103, v7, v103
	v_add_f32_dpp v111, v111, v111 row_mirror row_mask:0xf bank_mask:0xf bound_ctrl:1
	v_mul_f32_e32 v103, 0xbfb8aa3b, v103
	v_readlane_b32 s13, v111, 16
	v_readlane_b32 s12, v111, 0
	v_exp_f32_e32 v103, v103
	v_mov_b32_e32 v113, s13
	v_readlane_b32 s13, v111, 48
	v_add_f32_e32 v113, s12, v113
	v_readlane_b32 s12, v111, 32
	v_mov_b32_e32 v111, s13
	v_add_f32_e32 v103, 1.0, v103
	v_add_f32_e32 v111, s12, v111
	v_add_f32_e32 v111, v113, v111
	v_max_f32_e32 v111, 0x179abe15, v111
	v_rsq_f32_e32 v111, v111
	v_add_f32_e32 v94, v7, v94
	v_mul_f32_e32 v94, 0xbfb8aa3b, v94
	v_exp_f32_e32 v94, v94
	v_mul_f32_e32 v110, v110, v111
	v_add_f32_e32 v111, -1.0, v102
	v_mul_f32_e32 v102, v102, v110
	v_cvt_pk_bf16_f32 v100, -v110, s0
	v_fma_f32 v111, v3, v111, 1.0
	ds_write_b16 v109, v100 offset:36864
	v_cvt_pk_bf16_f32 v100, v102, s0
	v_mul_f32_e32 v101, v101, v111
	ds_write_b16 v109, v100 offset:45056
	v_cvt_pk_bf16_f32 v100, v106, s0
	v_mov_b32_e32 v102, v91
	v_cvt_pk_bf16_f32 v101, v101, s0
	ds_write_b16 v109, v100 offset:53248
	v_cvt_pk_bf16_f32 v100, v104, s0
	v_fmac_f32_e32 v102, v93, v23
	v_mov_b32_e32 v93, v90
	ds_write_b16 v109, v101 offset:20480
	ds_write_b16 v109, v100 offset:61440
	v_pk_add_f32 v[100:101], v[82:83], v[90:91] neg_lo:[0,1] neg_hi:[0,1]
	v_fmac_f32_e32 v93, v92, v19
	v_sub_f32_e32 v92, v129, v128
	v_fmac_f32_e32 v93, v100, v114
	v_fma_f32 v92, v92, v1, v128
	v_sub_f32_e32 v100, v127, v128
	v_fmac_f32_e32 v92, v100, v21
	v_add_f32_e32 v100, v11, v107
	v_mul_f32_e32 v100, 0xbfb8aa3b, v100
	v_exp_f32_e32 v100, v100
	v_fmac_f32_e32 v102, v101, v115
	v_cvt_pk_bf16_f32 v92, v92, s0
	ds_write_b16 v109, v92 offset:29184
	v_add_f32_e32 v100, 1.0, v100
	v_div_scale_f32 v101, s[12:13], v100, v100, s39
	v_rcp_f32_e32 v104, v101
	v_pk_add_f32 v[90:91], v[90:91], v[82:83] neg_lo:[0,1] neg_hi:[0,1]
	v_cvt_pk_bf16_f32 v102, v102, s0
	ds_write_b16 v109, v102 offset:12800
	v_fma_f32 v106, -v101, v104, 1.0
	v_fmac_f32_e32 v104, v106, v104
	v_div_scale_f32 v106, vcc, s39, v100, s39
	v_mul_f32_e32 v107, v106, v104
	v_fma_f32 v110, -v101, v107, v106
	v_fmac_f32_e32 v107, v110, v104
	v_fma_f32 v101, -v101, v107, v106
	v_div_fmas_f32 v101, v101, v104, v107
	v_div_fixup_f32 v100, v101, v100, s39
	v_add_f32_e32 v101, v9, v105
	v_mul_f32_e32 v101, 0xbfb8aa3b, v101
	v_exp_f32_e32 v101, v101
	v_mul_f32_e32 v100, 0x3fb8aa3b, v100
	v_exp_f32_e32 v100, v100
	v_add_f32_e32 v94, 1.0, v94
	v_add_f32_e32 v101, 1.0, v101
	v_div_scale_f32 v104, s[12:13], v101, v101, s39
	v_rcp_f32_e32 v105, v104
	v_sub_f32_e32 v100, 1.0, v100
	v_add_f32_e32 v84, v7, v84
	v_mul_f32_e32 v84, 0xbfb8aa3b, v84
	v_fma_f32 v106, -v104, v105, 1.0
	v_fmac_f32_e32 v105, v106, v105
	v_div_scale_f32 v106, vcc, s39, v101, s39
	v_mul_f32_e32 v107, v106, v105
	v_fma_f32 v110, -v104, v107, v106
	v_fmac_f32_e32 v107, v110, v105
	v_fma_f32 v104, -v104, v107, v106
	v_div_fmas_f32 v104, v104, v105, v107
	v_div_fixup_f32 v101, v104, v101, s39
	v_div_scale_f32 v104, s[12:13], v103, v103, 1.0
	v_rcp_f32_e32 v105, v104
	v_mul_f32_e32 v101, 0x3fb8aa3b, v101
	v_exp_f32_e32 v101, v101
	v_exp_f32_e32 v84, v84
	v_fma_f32 v106, -v104, v105, 1.0
	v_fmac_f32_e32 v105, v106, v105
	v_div_scale_f32 v106, vcc, 1.0, v103, 1.0
	v_mul_f32_e32 v107, v106, v105
	v_fma_f32 v110, -v104, v107, v106
	v_fmac_f32_e32 v107, v110, v105
	v_fma_f32 v104, -v104, v107, v106
	v_div_fmas_f32 v104, v104, v105, v107
	v_div_fixup_f32 v103, v104, v103, 1.0
	v_mul_f32_e32 v104, v5, v93
	v_mul_f32_e32 v105, v104, v104
	v_sub_f32_e32 v101, 1.0, v101
	v_add_f32_e32 v84, 1.0, v84
	v_mov_b32_dpp v105, v105 quad_perm:[1,0,3,2] row_mask:0xf bank_mask:0xf bound_ctrl:1
	v_fmac_f32_e32 v105, v104, v104
	v_add_f32_e32 v72, v7, v72
	v_mul_f32_e32 v72, 0xbfb8aa3b, v72
	v_add_f32_dpp v105, v105, v105 quad_perm:[2,3,0,1] row_mask:0xf bank_mask:0xf bound_ctrl:1
	v_exp_f32_e32 v72, v72
	v_add_f32_e32 v73, v7, v73
	v_add_f32_dpp v105, v105, v105 row_half_mirror row_mask:0xf bank_mask:0xf bound_ctrl:1
	v_mul_f32_e32 v73, 0xbfb8aa3b, v73
	v_add_f32_e32 v72, 1.0, v72
	v_add_f32_dpp v105, v105, v105 row_mirror row_mask:0xf bank_mask:0xf bound_ctrl:1
	v_exp_f32_e32 v73, v73
	v_readlane_b32 s13, v105, 16
	v_readlane_b32 s12, v105, 0
	v_add_f32_e32 v64, v9, v64
	v_mov_b32_e32 v106, s13
	v_readlane_b32 s13, v105, 48
	v_add_f32_e32 v106, s12, v106
	v_readlane_b32 s12, v105, 32
	v_mov_b32_e32 v105, s13
	v_add_f32_e32 v73, 1.0, v73
	v_add_f32_e32 v105, s12, v105
	v_add_f32_e32 v105, v106, v105
	v_max_f32_e32 v105, 0x179abe15, v105
	v_rsq_f32_e32 v105, v105
	v_mul_f32_e32 v64, 0xbfb8aa3b, v64
	v_exp_f32_e32 v64, v64
	v_add_f32_e32 v62, v7, v62
	v_mul_f32_e32 v104, v104, v105
	v_add_f32_e32 v105, -1.0, v103
	v_mul_f32_e32 v103, v103, v104
	v_cvt_pk_bf16_f32 v92, -v104, s0
	v_fma_f32 v105, v3, v105, 1.0
	ds_write_b16 v109, v92 offset:37376
	v_cvt_pk_bf16_f32 v92, v103, s0
	v_mul_f32_e32 v93, v93, v105
	ds_write_b16 v109, v92 offset:45568
	v_cvt_pk_bf16_f32 v92, v100, s0
	v_mov_b32_e32 v100, v83
	v_cvt_pk_bf16_f32 v93, v93, s0
	ds_write_b16 v109, v92 offset:53760
	v_cvt_pk_bf16_f32 v92, v101, s0
	v_fmac_f32_e32 v100, v91, v23
	v_mov_b32_e32 v91, v82
	ds_write_b16 v109, v93 offset:20992
	ds_write_b16 v109, v92 offset:61952
	v_pk_add_f32 v[92:93], v[80:81], v[82:83] neg_lo:[0,1] neg_hi:[0,1]
	v_fmac_f32_e32 v91, v90, v19
	v_sub_f32_e32 v90, v128, v127
	v_fmac_f32_e32 v91, v92, v114
	v_fma_f32 v90, v90, v1, v127
	v_sub_f32_e32 v92, v126, v127
	v_fmac_f32_e32 v90, v92, v21
	v_add_f32_e32 v92, v11, v98
	v_mul_f32_e32 v92, 0xbfb8aa3b, v92
	v_exp_f32_e32 v92, v92
	v_fmac_f32_e32 v100, v93, v115
	v_cvt_pk_bf16_f32 v90, v90, s0
	ds_write_b16 v109, v90 offset:29696
	v_add_f32_e32 v92, 1.0, v92
	v_div_scale_f32 v93, s[12:13], v92, v92, s39
	v_rcp_f32_e32 v98, v93
	v_pk_add_f32 v[82:83], v[82:83], v[80:81] neg_lo:[0,1] neg_hi:[0,1]
	v_add_f32_e32 v64, 1.0, v64
	v_mul_f32_e32 v62, 0xbfb8aa3b, v62
	v_fma_f32 v101, -v93, v98, 1.0
	v_fmac_f32_e32 v98, v101, v98
	v_div_scale_f32 v101, vcc, s39, v92, s39
	v_mul_f32_e32 v102, v101, v98
	v_fma_f32 v103, -v93, v102, v101
	v_fmac_f32_e32 v102, v103, v98
	v_fma_f32 v93, -v93, v102, v101
	v_div_fmas_f32 v93, v93, v98, v102
	v_div_fixup_f32 v92, v93, v92, s39
	v_add_f32_e32 v93, v9, v96
	v_mul_f32_e32 v93, 0xbfb8aa3b, v93
	v_exp_f32_e32 v93, v93
	v_mul_f32_e32 v92, 0x3fb8aa3b, v92
	v_exp_f32_e32 v92, v92
	v_exp_f32_e32 v62, v62
	v_add_f32_e32 v93, 1.0, v93
	v_div_scale_f32 v96, s[12:13], v93, v93, s39
	v_rcp_f32_e32 v98, v96
	v_sub_f32_e32 v92, 1.0, v92
	v_add_f32_e32 v62, 1.0, v62
	v_add_u32_e32 v108, 0x3000, v109
	v_fma_f32 v101, -v96, v98, 1.0
	v_fmac_f32_e32 v98, v101, v98
	v_div_scale_f32 v101, vcc, s39, v93, s39
	v_mul_f32_e32 v102, v101, v98
	v_fma_f32 v103, -v96, v102, v101
	v_fmac_f32_e32 v102, v103, v98
	v_fma_f32 v96, -v96, v102, v101
	v_div_fmas_f32 v96, v96, v98, v102
	v_div_fixup_f32 v93, v96, v93, s39
	v_div_scale_f32 v96, s[12:13], v94, v94, 1.0
	v_rcp_f32_e32 v98, v96
	v_mul_f32_e32 v93, 0x3fb8aa3b, v93
	v_exp_f32_e32 v93, v93
	v_add_f32_e32 v63, v7, v63
	v_fma_f32 v101, -v96, v98, 1.0
	v_fmac_f32_e32 v98, v101, v98
	v_div_scale_f32 v101, vcc, 1.0, v94, 1.0
	v_mul_f32_e32 v102, v101, v98
	v_fma_f32 v103, -v96, v102, v101
	v_fmac_f32_e32 v102, v103, v98
	v_fma_f32 v96, -v96, v102, v101
	v_div_fmas_f32 v96, v96, v98, v102
	v_div_fixup_f32 v94, v96, v94, 1.0
	v_mul_f32_e32 v96, v5, v91
	v_mul_f32_e32 v98, v96, v96
	v_sub_f32_e32 v93, 1.0, v93
	v_mul_f32_e32 v63, 0xbfb8aa3b, v63
	v_mov_b32_dpp v98, v98 quad_perm:[1,0,3,2] row_mask:0xf bank_mask:0xf bound_ctrl:1
	v_fmac_f32_e32 v98, v96, v96
	v_exp_f32_e32 v63, v63
	v_add_f32_e32 v56, v11, v56
	v_add_f32_dpp v98, v98, v98 quad_perm:[2,3,0,1] row_mask:0xf bank_mask:0xf bound_ctrl:1
	v_mul_f32_e32 v56, 0xbfb8aa3b, v56
	v_add_f32_e32 v63, 1.0, v63
	v_add_f32_dpp v98, v98, v98 row_half_mirror row_mask:0xf bank_mask:0xf bound_ctrl:1
	v_exp_f32_e32 v56, v56
	v_add_f32_e32 v54, v9, v54
	v_add_f32_dpp v98, v98, v98 row_mirror row_mask:0xf bank_mask:0xf bound_ctrl:1
	v_mul_f32_e32 v54, 0xbfb8aa3b, v54
	v_readlane_b32 s13, v98, 16
	v_readlane_b32 s12, v98, 0
	v_add_f32_e32 v56, 1.0, v56
	v_mov_b32_e32 v101, s13
	v_readlane_b32 s13, v98, 48
	v_add_f32_e32 v101, s12, v101
	v_readlane_b32 s12, v98, 32
	v_mov_b32_e32 v98, s13
	v_exp_f32_e32 v54, v54
	v_add_f32_e32 v98, s12, v98
	v_add_f32_e32 v98, v101, v98
	v_max_f32_e32 v98, 0x179abe15, v98
	v_rsq_f32_e32 v98, v98
	v_add_f32_e32 v54, 1.0, v54
	v_add_f32_e32 v52, v7, v52
	v_mul_f32_e32 v52, 0xbfb8aa3b, v52
	v_mul_f32_e32 v96, v96, v98
	v_add_f32_e32 v98, -1.0, v94
	v_mul_f32_e32 v94, v94, v96
	v_cvt_pk_bf16_f32 v90, -v96, s0
	v_fma_f32 v98, v3, v98, 1.0
	ds_write_b16 v109, v90 offset:37888
	v_cvt_pk_bf16_f32 v90, v94, s0
	v_mul_f32_e32 v91, v91, v98
	ds_write_b16 v109, v90 offset:46080
	v_cvt_pk_bf16_f32 v90, v92, s0
	v_mov_b32_e32 v92, v81
	v_cvt_pk_bf16_f32 v91, v91, s0
	ds_write_b16 v109, v90 offset:54272
	v_cvt_pk_bf16_f32 v90, v93, s0
	v_fmac_f32_e32 v92, v83, v23
	v_mov_b32_e32 v83, v80
	ds_write_b16 v109, v91 offset:21504
	ds_write_b16 v109, v90 offset:62464
	v_pk_add_f32 v[90:91], v[74:75], v[80:81] neg_lo:[0,1] neg_hi:[0,1]
	v_fmac_f32_e32 v83, v82, v19
	v_sub_f32_e32 v82, v127, v126
	v_fmac_f32_e32 v83, v90, v114
	v_fma_f32 v82, v82, v1, v126
	v_sub_f32_e32 v90, v125, v126
	v_fmac_f32_e32 v82, v90, v21
	v_add_f32_e32 v90, v11, v99
	v_mul_f32_e32 v90, 0xbfb8aa3b, v90
	v_exp_f32_e32 v90, v90
	v_fmac_f32_e32 v92, v91, v115
	v_cvt_pk_bf16_f32 v98, v100, s0
	ds_write_b16 v109, v98 offset:13312
	v_add_f32_e32 v90, 1.0, v90
	v_div_scale_f32 v91, s[12:13], v90, v90, s39
	v_rcp_f32_e32 v93, v91
	v_cvt_pk_bf16_f32 v82, v82, s0
	ds_write_b16 v109, v82 offset:30208
	v_pk_add_f32 v[80:81], v[80:81], v[74:75] neg_lo:[0,1] neg_hi:[0,1]
	v_fma_f32 v94, -v91, v93, 1.0
	v_fmac_f32_e32 v93, v94, v93
	v_div_scale_f32 v94, vcc, s39, v90, s39
	v_mul_f32_e32 v96, v94, v93
	v_fma_f32 v98, -v91, v96, v94
	v_fmac_f32_e32 v96, v98, v93
	v_fma_f32 v91, -v91, v96, v94
	v_div_fmas_f32 v91, v91, v93, v96
	v_div_fixup_f32 v90, v91, v90, s39
	v_add_f32_e32 v91, v9, v97
	v_mul_f32_e32 v91, 0xbfb8aa3b, v91
	v_exp_f32_e32 v91, v91
	v_mul_f32_e32 v90, 0x3fb8aa3b, v90
	v_exp_f32_e32 v90, v90
	v_cvt_pk_bf16_f32 v92, v92, s0
	v_add_f32_e32 v91, 1.0, v91
	v_div_scale_f32 v93, s[12:13], v91, v91, s39
	v_rcp_f32_e32 v94, v93
	v_sub_f32_e32 v90, 1.0, v90
	ds_write_b16 v109, v92 offset:13824
	v_exp_f32_e32 v52, v52
	v_fma_f32 v96, -v93, v94, 1.0
	v_fmac_f32_e32 v94, v96, v94
	v_div_scale_f32 v96, vcc, s39, v91, s39
	v_mul_f32_e32 v97, v96, v94
	v_fma_f32 v98, -v93, v97, v96
	v_fmac_f32_e32 v97, v98, v94
	v_fma_f32 v93, -v93, v97, v96
	v_div_fmas_f32 v93, v93, v94, v97
	v_div_fixup_f32 v91, v93, v91, s39
	v_add_f32_e32 v93, v7, v95
	v_mul_f32_e32 v93, 0xbfb8aa3b, v93
	v_exp_f32_e32 v93, v93
	v_mul_f32_e32 v91, 0x3fb8aa3b, v91
	v_exp_f32_e32 v91, v91
	v_add_f32_e32 v52, 1.0, v52
	v_add_f32_e32 v93, 1.0, v93
	v_div_scale_f32 v94, s[12:13], v93, v93, 1.0
	v_rcp_f32_e32 v95, v94
	v_sub_f32_e32 v91, 1.0, v91
	v_add_f32_e32 v53, v7, v53
	v_mul_f32_e32 v53, 0xbfb8aa3b, v53
	v_fma_f32 v96, -v94, v95, 1.0
	v_fmac_f32_e32 v95, v96, v95
	v_div_scale_f32 v96, vcc, 1.0, v93, 1.0
	v_mul_f32_e32 v97, v96, v95
	v_fma_f32 v98, -v94, v97, v96
	v_fmac_f32_e32 v97, v98, v95
	v_fma_f32 v94, -v94, v97, v96
	v_div_fmas_f32 v94, v94, v95, v97
	v_div_fixup_f32 v93, v94, v93, 1.0
	v_mul_f32_e32 v94, v5, v83
	v_mul_f32_e32 v95, v94, v94
	v_exp_f32_e32 v53, v53
	v_add_f32_e32 v46, v11, v46
	v_mov_b32_dpp v95, v95 quad_perm:[1,0,3,2] row_mask:0xf bank_mask:0xf bound_ctrl:1
	v_fmac_f32_e32 v95, v94, v94
	v_add_f32_e32 v53, 1.0, v53
	v_mul_f32_e32 v46, 0xbfb8aa3b, v46
	v_add_f32_dpp v95, v95, v95 quad_perm:[2,3,0,1] row_mask:0xf bank_mask:0xf bound_ctrl:1
	v_exp_f32_e32 v46, v46
	v_add_f32_e32 v44, v9, v44
	v_add_f32_dpp v95, v95, v95 row_half_mirror row_mask:0xf bank_mask:0xf bound_ctrl:1
	v_mul_f32_e32 v44, 0xbfb8aa3b, v44
	v_add_f32_e32 v46, 1.0, v46
	v_add_f32_dpp v95, v95, v95 row_mirror row_mask:0xf bank_mask:0xf bound_ctrl:1
	v_exp_f32_e32 v44, v44
	v_readlane_b32 s13, v95, 16
	v_readlane_b32 s12, v95, 0
	v_add_f32_e32 v42, v7, v42
	v_mov_b32_e32 v96, s13
	v_readlane_b32 s13, v95, 48
	v_add_f32_e32 v96, s12, v96
	v_readlane_b32 s12, v95, 32
	v_mov_b32_e32 v95, s13
	v_add_f32_e32 v44, 1.0, v44
	v_add_f32_e32 v95, s12, v95
	v_add_f32_e32 v95, v96, v95
	v_max_f32_e32 v95, 0x179abe15, v95
	v_rsq_f32_e32 v95, v95
	v_mul_f32_e32 v42, 0xbfb8aa3b, v42
	v_exp_f32_e32 v42, v42
	v_add_f32_e32 v43, v7, v43
	v_mul_f32_e32 v94, v94, v95
	v_add_f32_e32 v95, -1.0, v93
	v_mul_f32_e32 v93, v93, v94
	v_cvt_pk_bf16_f32 v82, -v94, s0
	v_fma_f32 v95, v3, v95, 1.0
	ds_write_b16 v109, v82 offset:38400
	v_cvt_pk_bf16_f32 v82, v93, s0
	v_mul_f32_e32 v83, v83, v95
	ds_write_b16 v109, v82 offset:46592
	v_cvt_pk_bf16_f32 v82, v90, s0
	v_mov_b32_e32 v90, v75
	v_cvt_pk_bf16_f32 v83, v83, s0
	ds_write_b16 v109, v82 offset:54784
	v_cvt_pk_bf16_f32 v82, v91, s0
	v_fmac_f32_e32 v90, v81, v23
	v_mov_b32_e32 v81, v74
	ds_write_b16 v109, v83 offset:22016
	ds_write_b16 v109, v82 offset:62976
	v_pk_add_f32 v[82:83], v[70:71], v[74:75] neg_lo:[0,1] neg_hi:[0,1]
	v_fmac_f32_e32 v81, v80, v19
	v_sub_f32_e32 v80, v126, v125
	v_fmac_f32_e32 v81, v82, v114
	v_fma_f32 v80, v80, v1, v125
	v_sub_f32_e32 v82, v124, v125
	v_fmac_f32_e32 v80, v82, v21
	v_add_f32_e32 v82, v11, v88
	v_mul_f32_e32 v82, 0xbfb8aa3b, v82
	v_exp_f32_e32 v82, v82
	v_fmac_f32_e32 v90, v83, v115
	v_cvt_pk_bf16_f32 v80, v80, s0
	ds_write_b16 v109, v80 offset:30720
	v_add_f32_e32 v82, 1.0, v82
	v_div_scale_f32 v83, s[12:13], v82, v82, s39
	v_rcp_f32_e32 v88, v83
	v_pk_add_f32 v[74:75], v[74:75], v[70:71] neg_lo:[0,1] neg_hi:[0,1]
	v_add_f32_e32 v42, 1.0, v42
	v_mul_f32_e32 v43, 0xbfb8aa3b, v43
	v_fma_f32 v91, -v83, v88, 1.0
	v_fmac_f32_e32 v88, v91, v88
	v_div_scale_f32 v91, vcc, s39, v82, s39
	v_mul_f32_e32 v92, v91, v88
	v_fma_f32 v93, -v83, v92, v91
	v_fmac_f32_e32 v92, v93, v88
	v_fma_f32 v83, -v83, v92, v91
	v_div_fmas_f32 v83, v83, v88, v92
	v_div_fixup_f32 v82, v83, v82, s39
	v_add_f32_e32 v83, v9, v86
	v_mul_f32_e32 v83, 0xbfb8aa3b, v83
	v_exp_f32_e32 v83, v83
	v_mul_f32_e32 v82, 0x3fb8aa3b, v82
	v_exp_f32_e32 v82, v82
	v_exp_f32_e32 v43, v43
	v_add_f32_e32 v83, 1.0, v83
	v_div_scale_f32 v86, s[12:13], v83, v83, s39
	v_rcp_f32_e32 v88, v86
	v_sub_f32_e32 v82, 1.0, v82
	v_add_f32_e32 v43, 1.0, v43
	v_add_f32_e32 v36, v11, v36
	v_fma_f32 v91, -v86, v88, 1.0
	v_fmac_f32_e32 v88, v91, v88
	v_div_scale_f32 v91, vcc, s39, v83, s39
	v_mul_f32_e32 v92, v91, v88
	v_fma_f32 v93, -v86, v92, v91
	v_fmac_f32_e32 v92, v93, v88
	v_fma_f32 v86, -v86, v92, v91
	v_div_fmas_f32 v86, v86, v88, v92
	v_div_fixup_f32 v83, v86, v83, s39
	v_div_scale_f32 v86, s[12:13], v84, v84, 1.0
	v_rcp_f32_e32 v88, v86
	v_mul_f32_e32 v83, 0x3fb8aa3b, v83
	v_exp_f32_e32 v83, v83
	v_mul_f32_e32 v36, 0xbfb8aa3b, v36
	v_fma_f32 v91, -v86, v88, 1.0
	v_fmac_f32_e32 v88, v91, v88
	v_div_scale_f32 v91, vcc, 1.0, v84, 1.0
	v_mul_f32_e32 v92, v91, v88
	v_fma_f32 v93, -v86, v92, v91
	v_fmac_f32_e32 v92, v93, v88
	v_fma_f32 v86, -v86, v92, v91
	v_div_fmas_f32 v86, v86, v88, v92
	v_div_fixup_f32 v84, v86, v84, 1.0
	v_mul_f32_e32 v86, v5, v81
	v_mul_f32_e32 v88, v86, v86
	v_sub_f32_e32 v83, 1.0, v83
	v_exp_f32_e32 v36, v36
	v_mov_b32_dpp v88, v88 quad_perm:[1,0,3,2] row_mask:0xf bank_mask:0xf bound_ctrl:1
	v_fmac_f32_e32 v88, v86, v86
	v_add_f32_e32 v34, v9, v34
	v_add_f32_e32 v36, 1.0, v36
	v_add_f32_dpp v88, v88, v88 quad_perm:[2,3,0,1] row_mask:0xf bank_mask:0xf bound_ctrl:1
	v_mul_f32_e32 v34, 0xbfb8aa3b, v34
	v_exp_f32_e32 v34, v34
	v_add_f32_dpp v88, v88, v88 row_half_mirror row_mask:0xf bank_mask:0xf bound_ctrl:1
	v_add_f32_e32 v30, v7, v30
	v_mul_f32_e32 v30, 0xbfb8aa3b, v30
	v_add_f32_dpp v88, v88, v88 row_mirror row_mask:0xf bank_mask:0xf bound_ctrl:1
	v_add_f32_e32 v34, 1.0, v34
	v_readlane_b32 s13, v88, 16
	v_readlane_b32 s12, v88, 0
	v_exp_f32_e32 v30, v30
	v_mov_b32_e32 v91, s13
	v_readlane_b32 s13, v88, 48
	v_add_f32_e32 v91, s12, v91
	v_readlane_b32 s12, v88, 32
	v_mov_b32_e32 v88, s13
	v_add_f32_e32 v30, 1.0, v30
	v_add_f32_e32 v88, s12, v88
	v_add_f32_e32 v88, v91, v88
	v_max_f32_e32 v88, 0x179abe15, v88
	v_rsq_f32_e32 v88, v88
	v_sub_f32_e32 v17, v17, v13
	v_pk_add_f32 v[28:29], v[28:29], v[24:25] neg_lo:[0,1] neg_hi:[0,1]
	v_cvt_pk_bf16_f32 v111, v112, s0
	v_mul_f32_e32 v86, v86, v88
	v_add_f32_e32 v88, -1.0, v84
	v_mul_f32_e32 v84, v84, v86
	v_cvt_pk_bf16_f32 v80, -v86, s0
	v_fma_f32 v88, v3, v88, 1.0
	ds_write_b16 v109, v80 offset:38912
	v_cvt_pk_bf16_f32 v80, v84, s0
	v_mul_f32_e32 v81, v81, v88
	ds_write_b16 v109, v80 offset:47104
	v_cvt_pk_bf16_f32 v80, v82, s0
	v_mov_b32_e32 v82, v71
	v_cvt_pk_bf16_f32 v81, v81, s0
	ds_write_b16 v109, v80 offset:55296
	v_cvt_pk_bf16_f32 v80, v83, s0
	v_fmac_f32_e32 v82, v75, v23
	v_mov_b32_e32 v75, v70
	ds_write_b16 v109, v81 offset:22528
	ds_write_b16 v109, v80 offset:63488
	v_pk_add_f32 v[80:81], v[66:67], v[70:71] neg_lo:[0,1] neg_hi:[0,1]
	v_fmac_f32_e32 v75, v74, v19
	v_sub_f32_e32 v74, v125, v124
	v_fmac_f32_e32 v75, v80, v114
	v_fma_f32 v74, v74, v1, v124
	v_sub_f32_e32 v80, v123, v124
	v_fmac_f32_e32 v74, v80, v21
	v_add_f32_e32 v80, v11, v89
	v_mul_f32_e32 v80, 0xbfb8aa3b, v80
	v_exp_f32_e32 v80, v80
	v_fmac_f32_e32 v82, v81, v115
	v_cvt_pk_bf16_f32 v88, v90, s0
	ds_write_b16 v109, v88 offset:14336
	v_add_f32_e32 v80, 1.0, v80
	v_div_scale_f32 v81, s[12:13], v80, v80, s39
	v_rcp_f32_e32 v83, v81
	v_cvt_pk_bf16_f32 v74, v74, s0
	ds_write_b16 v109, v74 offset:31232
	v_pk_add_f32 v[70:71], v[70:71], v[66:67] neg_lo:[0,1] neg_hi:[0,1]
	v_fma_f32 v84, -v81, v83, 1.0
	v_fmac_f32_e32 v83, v84, v83
	v_div_scale_f32 v84, vcc, s39, v80, s39
	v_mul_f32_e32 v86, v84, v83
	v_fma_f32 v88, -v81, v86, v84
	v_fmac_f32_e32 v86, v88, v83
	v_fma_f32 v81, -v81, v86, v84
	v_div_fmas_f32 v81, v81, v83, v86
	v_div_fixup_f32 v80, v81, v80, s39
	v_add_f32_e32 v81, v9, v87
	v_mul_f32_e32 v81, 0xbfb8aa3b, v81
	v_exp_f32_e32 v81, v81
	v_mul_f32_e32 v80, 0x3fb8aa3b, v80
	v_exp_f32_e32 v80, v80
	v_cvt_pk_bf16_f32 v82, v82, s0
	v_add_f32_e32 v81, 1.0, v81
	v_div_scale_f32 v83, s[12:13], v81, v81, s39
	v_rcp_f32_e32 v84, v83
	v_sub_f32_e32 v80, 1.0, v80
	ds_write_b16 v109, v82 offset:14848
	ds_write_b16 v109, v111 offset:12288
	v_fma_f32 v86, -v83, v84, 1.0
	v_fmac_f32_e32 v84, v86, v84
	v_div_scale_f32 v86, vcc, s39, v81, s39
	v_mul_f32_e32 v87, v86, v84
	v_fma_f32 v88, -v83, v87, v86
	v_fmac_f32_e32 v87, v88, v84
	v_fma_f32 v83, -v83, v87, v86
	v_div_fmas_f32 v83, v83, v84, v87
	v_div_fixup_f32 v81, v83, v81, s39
	v_add_f32_e32 v83, v7, v85
	v_mul_f32_e32 v83, 0xbfb8aa3b, v83
	v_exp_f32_e32 v83, v83
	v_mul_f32_e32 v81, 0x3fb8aa3b, v81
	v_exp_f32_e32 v81, v81
	v_add_f32_e32 v7, v7, v31
	v_add_f32_e32 v83, 1.0, v83
	v_div_scale_f32 v84, s[12:13], v83, v83, 1.0
	v_rcp_f32_e32 v85, v84
	v_sub_f32_e32 v81, 1.0, v81
	v_mul_f32_e32 v7, 0xbfb8aa3b, v7
	v_exp_f32_e32 v7, v7
	v_fma_f32 v86, -v84, v85, 1.0
	v_fmac_f32_e32 v85, v86, v85
	v_div_scale_f32 v86, vcc, 1.0, v83, 1.0
	v_mul_f32_e32 v87, v86, v85
	v_fma_f32 v88, -v84, v87, v86
	v_fmac_f32_e32 v87, v88, v85
	v_fma_f32 v84, -v84, v87, v86
	v_div_fmas_f32 v84, v84, v85, v87
	v_div_fixup_f32 v83, v84, v83, 1.0
	v_mul_f32_e32 v84, v5, v75
	v_mul_f32_e32 v85, v84, v84
	v_add_f32_e32 v7, 1.0, v7
	s_add_i32 s19, s19, s38
	v_mov_b32_dpp v85, v85 quad_perm:[1,0,3,2] row_mask:0xf bank_mask:0xf bound_ctrl:1
	v_fmac_f32_e32 v85, v84, v84
	s_cmpk_gt_i32 s19, 0xbff
	s_nop 0
	v_add_f32_dpp v85, v85, v85 quad_perm:[2,3,0,1] row_mask:0xf bank_mask:0xf bound_ctrl:1
	s_nop 1
	v_add_f32_dpp v85, v85, v85 row_half_mirror row_mask:0xf bank_mask:0xf bound_ctrl:1
	s_nop 1
	v_add_f32_dpp v85, v85, v85 row_mirror row_mask:0xf bank_mask:0xf bound_ctrl:1
	s_nop 0
	v_readlane_b32 s13, v85, 16
	v_readlane_b32 s12, v85, 0
	s_nop 0
	v_mov_b32_e32 v86, s13
	v_readlane_b32 s13, v85, 48
	v_add_f32_e32 v86, s12, v86
	v_readlane_b32 s12, v85, 32
	v_mov_b32_e32 v85, s13
	s_nop 0
	v_add_f32_e32 v85, s12, v85
	v_add_f32_e32 v85, v86, v85
	v_max_f32_e32 v85, 0x179abe15, v85
	v_rsq_f32_e32 v85, v85
	s_nop 0
	v_mul_f32_e32 v84, v84, v85
	v_add_f32_e32 v85, -1.0, v83
	v_mul_f32_e32 v83, v83, v84
	v_cvt_pk_bf16_f32 v74, -v84, s0
	v_fma_f32 v85, v3, v85, 1.0
	ds_write_b16 v109, v74 offset:39424
	v_cvt_pk_bf16_f32 v74, v83, s0
	v_mul_f32_e32 v75, v75, v85
	ds_write_b16 v109, v74 offset:47616
	v_cvt_pk_bf16_f32 v74, v80, s0
	v_mov_b32_e32 v80, v67
	v_cvt_pk_bf16_f32 v75, v75, s0
	ds_write_b16 v109, v74 offset:55808
	v_cvt_pk_bf16_f32 v74, v81, s0
	v_fmac_f32_e32 v80, v71, v23
	v_mov_b32_e32 v71, v66
	ds_write_b16 v109, v75 offset:23040
	ds_write_b16 v109, v74 offset:64000
	v_pk_add_f32 v[74:75], v[60:61], v[66:67] neg_lo:[0,1] neg_hi:[0,1]
	v_fmac_f32_e32 v71, v70, v19
	v_sub_f32_e32 v70, v124, v123
	v_fmac_f32_e32 v71, v74, v114
	v_fma_f32 v70, v70, v1, v123
	v_sub_f32_e32 v74, v122, v123
	v_fmac_f32_e32 v70, v74, v21
	v_add_f32_e32 v74, v11, v78
	v_mul_f32_e32 v74, 0xbfb8aa3b, v74
	v_exp_f32_e32 v74, v74
	v_fmac_f32_e32 v80, v75, v115
	v_cvt_pk_bf16_f32 v70, v70, s0
	ds_write_b16 v109, v70 offset:31744
	v_add_f32_e32 v74, 1.0, v74
	v_div_scale_f32 v75, s[12:13], v74, v74, s39
	v_rcp_f32_e32 v78, v75
	v_pk_add_f32 v[66:67], v[66:67], v[60:61] neg_lo:[0,1] neg_hi:[0,1]
	v_fma_f32 v81, -v75, v78, 1.0
	v_fmac_f32_e32 v78, v81, v78
	v_div_scale_f32 v81, vcc, s39, v74, s39
	v_mul_f32_e32 v82, v81, v78
	v_fma_f32 v83, -v75, v82, v81
	v_fmac_f32_e32 v82, v83, v78
	v_fma_f32 v75, -v75, v82, v81
	v_div_fmas_f32 v75, v75, v78, v82
	v_div_fixup_f32 v74, v75, v74, s39
	v_add_f32_e32 v75, v9, v76
	v_mul_f32_e32 v75, 0xbfb8aa3b, v75
	v_exp_f32_e32 v75, v75
	v_mul_f32_e32 v74, 0x3fb8aa3b, v74
	v_exp_f32_e32 v74, v74
	v_add_f32_e32 v75, 1.0, v75
	v_div_scale_f32 v76, s[12:13], v75, v75, s39
	v_rcp_f32_e32 v78, v76
	v_sub_f32_e32 v74, 1.0, v74
	v_fma_f32 v81, -v76, v78, 1.0
	v_fmac_f32_e32 v78, v81, v78
	v_div_scale_f32 v81, vcc, s39, v75, s39
	v_mul_f32_e32 v82, v81, v78
	v_fma_f32 v83, -v76, v82, v81
	v_fmac_f32_e32 v82, v83, v78
	v_fma_f32 v76, -v76, v82, v81
	v_div_fmas_f32 v76, v76, v78, v82
	v_div_fixup_f32 v75, v76, v75, s39
	v_div_scale_f32 v76, s[12:13], v72, v72, 1.0
	v_rcp_f32_e32 v78, v76
	v_mul_f32_e32 v75, 0x3fb8aa3b, v75
	v_exp_f32_e32 v75, v75
	v_fma_f32 v81, -v76, v78, 1.0
	v_fmac_f32_e32 v78, v81, v78
	v_div_scale_f32 v81, vcc, 1.0, v72, 1.0
	v_mul_f32_e32 v82, v81, v78
	v_fma_f32 v83, -v76, v82, v81
	v_fmac_f32_e32 v82, v83, v78
	v_fma_f32 v76, -v76, v82, v81
	v_div_fmas_f32 v76, v76, v78, v82
	v_div_fixup_f32 v72, v76, v72, 1.0
	v_mul_f32_e32 v76, v5, v71
	v_mul_f32_e32 v78, v76, v76
	v_sub_f32_e32 v75, 1.0, v75
	s_nop 0
	v_mov_b32_dpp v78, v78 quad_perm:[1,0,3,2] row_mask:0xf bank_mask:0xf bound_ctrl:1
	v_fmac_f32_e32 v78, v76, v76
	s_nop 1
	v_add_f32_dpp v78, v78, v78 quad_perm:[2,3,0,1] row_mask:0xf bank_mask:0xf bound_ctrl:1
	s_nop 1
	v_add_f32_dpp v78, v78, v78 row_half_mirror row_mask:0xf bank_mask:0xf bound_ctrl:1
	s_nop 1
	v_add_f32_dpp v78, v78, v78 row_mirror row_mask:0xf bank_mask:0xf bound_ctrl:1
	s_nop 0
	v_readlane_b32 s13, v78, 16
	v_readlane_b32 s12, v78, 0
	s_nop 0
	v_mov_b32_e32 v81, s13
	v_readlane_b32 s13, v78, 48
	v_add_f32_e32 v81, s12, v81
	v_readlane_b32 s12, v78, 32
	v_mov_b32_e32 v78, s13
	s_nop 0
	v_add_f32_e32 v78, s12, v78
	v_add_f32_e32 v78, v81, v78
	v_max_f32_e32 v78, 0x179abe15, v78
	v_rsq_f32_e32 v78, v78
	s_nop 0
	v_mul_f32_e32 v76, v76, v78
	v_add_f32_e32 v78, -1.0, v72
	v_mul_f32_e32 v72, v72, v76
	v_cvt_pk_bf16_f32 v70, -v76, s0
	v_fma_f32 v78, v3, v78, 1.0
	ds_write_b16 v109, v70 offset:39936
	v_cvt_pk_bf16_f32 v70, v72, s0
	v_mul_f32_e32 v71, v71, v78
	ds_write_b16 v109, v70 offset:48128
	v_cvt_pk_bf16_f32 v70, v74, s0
	v_mov_b32_e32 v72, v61
	v_cvt_pk_bf16_f32 v71, v71, s0
	ds_write_b16 v109, v70 offset:56320
	v_cvt_pk_bf16_f32 v70, v75, s0
	v_fmac_f32_e32 v72, v67, v23
	v_mov_b32_e32 v67, v60
	ds_write_b16 v109, v71 offset:23552
	ds_write_b16 v109, v70 offset:64512
	v_pk_add_f32 v[70:71], v[58:59], v[60:61] neg_lo:[0,1] neg_hi:[0,1]
	v_fmac_f32_e32 v67, v66, v19
	v_sub_f32_e32 v66, v123, v122
	v_fmac_f32_e32 v67, v70, v114
	v_fma_f32 v66, v66, v1, v122
	v_sub_f32_e32 v70, v121, v122
	v_fmac_f32_e32 v66, v70, v21
	v_add_f32_e32 v70, v11, v79
	v_mul_f32_e32 v70, 0xbfb8aa3b, v70
	v_exp_f32_e32 v70, v70
	v_fmac_f32_e32 v72, v71, v115
	v_cvt_pk_bf16_f32 v78, v80, s0
	ds_write_b16 v109, v78 offset:15360
	v_add_f32_e32 v70, 1.0, v70
	v_div_scale_f32 v71, s[12:13], v70, v70, s39
	v_rcp_f32_e32 v74, v71
	v_cvt_pk_bf16_f32 v66, v66, s0
	ds_write_b16 v109, v66 offset:32256
	v_pk_add_f32 v[60:61], v[60:61], v[58:59] neg_lo:[0,1] neg_hi:[0,1]
	v_fma_f32 v75, -v71, v74, 1.0
	v_fmac_f32_e32 v74, v75, v74
	v_div_scale_f32 v75, vcc, s39, v70, s39
	v_mul_f32_e32 v76, v75, v74
	v_fma_f32 v78, -v71, v76, v75
	v_fmac_f32_e32 v76, v78, v74
	v_fma_f32 v71, -v71, v76, v75
	v_div_fmas_f32 v71, v71, v74, v76
	v_div_fixup_f32 v70, v71, v70, s39
	v_add_f32_e32 v71, v9, v77
	v_mul_f32_e32 v71, 0xbfb8aa3b, v71
	v_exp_f32_e32 v71, v71
	v_mul_f32_e32 v70, 0x3fb8aa3b, v70
	v_exp_f32_e32 v70, v70
	v_cvt_pk_bf16_f32 v72, v72, s0
	v_add_f32_e32 v71, 1.0, v71
	v_div_scale_f32 v74, s[12:13], v71, v71, s39
	v_rcp_f32_e32 v75, v74
	v_sub_f32_e32 v70, 1.0, v70
	ds_write_b16 v109, v72 offset:15872
	v_fma_f32 v76, -v74, v75, 1.0
	v_fmac_f32_e32 v75, v76, v75
	v_div_scale_f32 v76, vcc, s39, v71, s39
	v_mul_f32_e32 v77, v76, v75
	v_fma_f32 v78, -v74, v77, v76
	v_fmac_f32_e32 v77, v78, v75
	v_fma_f32 v74, -v74, v77, v76
	v_div_fmas_f32 v74, v74, v75, v77
	v_div_fixup_f32 v71, v74, v71, s39
	v_div_scale_f32 v74, s[12:13], v73, v73, 1.0
	v_rcp_f32_e32 v75, v74
	v_mul_f32_e32 v71, 0x3fb8aa3b, v71
	v_exp_f32_e32 v71, v71
	v_fma_f32 v76, -v74, v75, 1.0
	v_fmac_f32_e32 v75, v76, v75
	v_div_scale_f32 v76, vcc, 1.0, v73, 1.0
	v_mul_f32_e32 v77, v76, v75
	v_fma_f32 v78, -v74, v77, v76
	v_fmac_f32_e32 v77, v78, v75
	v_fma_f32 v74, -v74, v77, v76
	v_div_fmas_f32 v74, v74, v75, v77
	v_div_fixup_f32 v73, v74, v73, 1.0
	v_mul_f32_e32 v74, v5, v67
	v_mul_f32_e32 v75, v74, v74
	v_sub_f32_e32 v71, 1.0, v71
	s_nop 0
	v_mov_b32_dpp v75, v75 quad_perm:[1,0,3,2] row_mask:0xf bank_mask:0xf bound_ctrl:1
	v_fmac_f32_e32 v75, v74, v74
	s_nop 1
	v_add_f32_dpp v75, v75, v75 quad_perm:[2,3,0,1] row_mask:0xf bank_mask:0xf bound_ctrl:1
	s_nop 1
	v_add_f32_dpp v75, v75, v75 row_half_mirror row_mask:0xf bank_mask:0xf bound_ctrl:1
	s_nop 1
	v_add_f32_dpp v75, v75, v75 row_mirror row_mask:0xf bank_mask:0xf bound_ctrl:1
	s_nop 0
	v_readlane_b32 s13, v75, 16
	v_readlane_b32 s12, v75, 0
	s_nop 0
	v_mov_b32_e32 v76, s13
	v_readlane_b32 s13, v75, 48
	v_add_f32_e32 v76, s12, v76
	v_readlane_b32 s12, v75, 32
	v_mov_b32_e32 v75, s13
	s_nop 0
	v_add_f32_e32 v75, s12, v75
	v_add_f32_e32 v75, v76, v75
	v_max_f32_e32 v75, 0x179abe15, v75
	v_rsq_f32_e32 v75, v75
	s_nop 0
	v_mul_f32_e32 v74, v74, v75
	v_add_f32_e32 v75, -1.0, v73
	v_mul_f32_e32 v73, v73, v74
	v_cvt_pk_bf16_f32 v66, -v74, s0
	v_fma_f32 v75, v3, v75, 1.0
	ds_write_b16 v109, v66 offset:40448
	v_cvt_pk_bf16_f32 v66, v73, s0
	v_mul_f32_e32 v67, v67, v75
	ds_write_b16 v109, v66 offset:48640
	v_cvt_pk_bf16_f32 v66, v70, s0
	v_mov_b32_e32 v70, v59
	v_cvt_pk_bf16_f32 v67, v67, s0
	ds_write_b16 v109, v66 offset:56832
	v_cvt_pk_bf16_f32 v66, v71, s0
	v_fmac_f32_e32 v70, v61, v23
	v_mov_b32_e32 v61, v58
	ds_write_b16 v109, v67 offset:24064
	ds_write_b16 v109, v66 offset:65024
	v_pk_add_f32 v[66:67], v[50:51], v[58:59] neg_lo:[0,1] neg_hi:[0,1]
	v_fmac_f32_e32 v61, v60, v19
	v_sub_f32_e32 v60, v122, v121
	v_fmac_f32_e32 v61, v66, v114
	v_fma_f32 v60, v60, v1, v121
	v_sub_f32_e32 v66, v120, v121
	v_fmac_f32_e32 v60, v66, v21
	v_add_f32_e32 v66, v11, v68
	v_mul_f32_e32 v66, 0xbfb8aa3b, v66
	v_exp_f32_e32 v66, v66
	v_fmac_f32_e32 v70, v67, v115
	v_cvt_pk_bf16_f32 v60, v60, s0
	ds_write_b16 v109, v60 offset:32768
	v_add_f32_e32 v66, 1.0, v66
	v_div_scale_f32 v67, s[12:13], v66, v66, s39
	v_rcp_f32_e32 v68, v67
	v_pk_add_f32 v[58:59], v[58:59], v[50:51] neg_lo:[0,1] neg_hi:[0,1]
	v_fma_f32 v71, -v67, v68, 1.0
	v_fmac_f32_e32 v68, v71, v68
	v_div_scale_f32 v71, vcc, s39, v66, s39
	v_mul_f32_e32 v72, v71, v68
	v_fma_f32 v73, -v67, v72, v71
	v_fmac_f32_e32 v72, v73, v68
	v_fma_f32 v67, -v67, v72, v71
	v_div_fmas_f32 v67, v67, v68, v72
	v_div_fixup_f32 v66, v67, v66, s39
	v_div_scale_f32 v67, s[12:13], v64, v64, s39
	v_rcp_f32_e32 v68, v67
	v_mul_f32_e32 v66, 0x3fb8aa3b, v66
	v_exp_f32_e32 v66, v66
	v_fma_f32 v71, -v67, v68, 1.0
	v_fmac_f32_e32 v68, v71, v68
	v_div_scale_f32 v71, vcc, s39, v64, s39
	v_mul_f32_e32 v72, v71, v68
	v_fma_f32 v73, -v67, v72, v71
	v_fmac_f32_e32 v72, v73, v68
	v_fma_f32 v67, -v67, v72, v71
	v_div_fmas_f32 v67, v67, v68, v72
	v_div_fixup_f32 v64, v67, v64, s39
	v_div_scale_f32 v67, s[12:13], v62, v62, 1.0
	v_rcp_f32_e32 v68, v67
	v_mul_f32_e32 v64, 0x3fb8aa3b, v64
	v_exp_f32_e32 v64, v64
	v_sub_f32_e32 v66, 1.0, v66
	v_fma_f32 v71, -v67, v68, 1.0
	v_fmac_f32_e32 v68, v71, v68
	v_div_scale_f32 v71, vcc, 1.0, v62, 1.0
	v_mul_f32_e32 v72, v71, v68
	v_fma_f32 v73, -v67, v72, v71
	v_fmac_f32_e32 v72, v73, v68
	v_fma_f32 v67, -v67, v72, v71
	v_div_fmas_f32 v67, v67, v68, v72
	v_div_fixup_f32 v62, v67, v62, 1.0
	v_mul_f32_e32 v67, v5, v61
	v_mul_f32_e32 v68, v67, v67
	v_sub_f32_e32 v64, 1.0, v64
	s_nop 0
	v_mov_b32_dpp v68, v68 quad_perm:[1,0,3,2] row_mask:0xf bank_mask:0xf bound_ctrl:1
	v_fmac_f32_e32 v68, v67, v67
	s_nop 1
	v_add_f32_dpp v68, v68, v68 quad_perm:[2,3,0,1] row_mask:0xf bank_mask:0xf bound_ctrl:1
	s_nop 1
	v_add_f32_dpp v68, v68, v68 row_half_mirror row_mask:0xf bank_mask:0xf bound_ctrl:1
	s_nop 1
	v_add_f32_dpp v68, v68, v68 row_mirror row_mask:0xf bank_mask:0xf bound_ctrl:1
	s_nop 0
	v_readlane_b32 s13, v68, 16
	v_readlane_b32 s12, v68, 0
	s_nop 0
	v_mov_b32_e32 v71, s13
	v_readlane_b32 s13, v68, 48
	v_add_f32_e32 v71, s12, v71
	v_readlane_b32 s12, v68, 32
	v_mov_b32_e32 v68, s13
	s_nop 0
	v_add_f32_e32 v68, s12, v68
	v_add_f32_e32 v68, v71, v68
	v_max_f32_e32 v68, 0x179abe15, v68
	v_rsq_f32_e32 v68, v68
	s_nop 0
	v_mul_f32_e32 v67, v67, v68
	v_add_f32_e32 v68, -1.0, v62
	v_mul_f32_e32 v62, v62, v67
	v_cvt_pk_bf16_f32 v60, -v67, s0
	v_fma_f32 v68, v3, v68, 1.0
	ds_write_b16 v109, v60 offset:40960
	v_cvt_pk_bf16_f32 v60, v62, s0
	v_mul_f32_e32 v61, v61, v68
	ds_write_b16 v109, v60 offset:49152
	v_cvt_pk_bf16_f32 v60, v66, s0
	v_mov_b32_e32 v62, v51
	v_cvt_pk_bf16_f32 v61, v61, s0
	ds_write_b16 v109, v60 offset:57344
	v_cvt_pk_bf16_f32 v60, v64, s0
	v_fmac_f32_e32 v62, v59, v23
	v_mov_b32_e32 v59, v50
	ds_write_b16 v109, v61 offset:24576
	ds_write_b16 v108, v60 offset:53248
	v_pk_add_f32 v[60:61], v[48:49], v[50:51] neg_lo:[0,1] neg_hi:[0,1]
	v_fmac_f32_e32 v59, v58, v19
	v_sub_f32_e32 v58, v121, v120
	v_fmac_f32_e32 v59, v60, v114
	v_fma_f32 v58, v58, v1, v120
	v_sub_f32_e32 v60, v119, v120
	v_fmac_f32_e32 v58, v60, v21
	v_add_f32_e32 v60, v11, v69
	v_mul_f32_e32 v60, 0xbfb8aa3b, v60
	v_exp_f32_e32 v60, v60
	v_fmac_f32_e32 v62, v61, v115
	v_cvt_pk_bf16_f32 v68, v70, s0
	ds_write_b16 v109, v68 offset:16384
	v_add_f32_e32 v60, 1.0, v60
	v_div_scale_f32 v61, s[12:13], v60, v60, s39
	v_rcp_f32_e32 v64, v61
	v_cvt_pk_bf16_f32 v58, v58, s0
	ds_write_b16 v109, v58 offset:33280
	v_pk_add_f32 v[50:51], v[50:51], v[48:49] neg_lo:[0,1] neg_hi:[0,1]
	v_fma_f32 v66, -v61, v64, 1.0
	v_fmac_f32_e32 v64, v66, v64
	v_div_scale_f32 v66, vcc, s39, v60, s39
	v_mul_f32_e32 v67, v66, v64
	v_fma_f32 v68, -v61, v67, v66
	v_fmac_f32_e32 v67, v68, v64
	v_fma_f32 v61, -v61, v67, v66
	v_div_fmas_f32 v61, v61, v64, v67
	v_div_fixup_f32 v60, v61, v60, s39
	v_add_f32_e32 v61, v9, v65
	v_mul_f32_e32 v61, 0xbfb8aa3b, v61
	v_exp_f32_e32 v61, v61
	v_mul_f32_e32 v60, 0x3fb8aa3b, v60
	v_exp_f32_e32 v60, v60
	v_cvt_pk_bf16_f32 v62, v62, s0
	v_add_f32_e32 v61, 1.0, v61
	v_div_scale_f32 v64, s[12:13], v61, v61, s39
	v_rcp_f32_e32 v65, v64
	v_sub_f32_e32 v60, 1.0, v60
	ds_write_b16 v109, v62 offset:16896
	v_fma_f32 v66, -v64, v65, 1.0
	v_fmac_f32_e32 v65, v66, v65
	v_div_scale_f32 v66, vcc, s39, v61, s39
	v_mul_f32_e32 v67, v66, v65
	v_fma_f32 v68, -v64, v67, v66
	v_fmac_f32_e32 v67, v68, v65
	v_fma_f32 v64, -v64, v67, v66
	v_div_fmas_f32 v64, v64, v65, v67
	v_div_fixup_f32 v61, v64, v61, s39
	v_div_scale_f32 v64, s[12:13], v63, v63, 1.0
	v_rcp_f32_e32 v65, v64
	v_mul_f32_e32 v61, 0x3fb8aa3b, v61
	v_exp_f32_e32 v61, v61
	v_fma_f32 v66, -v64, v65, 1.0
	v_fmac_f32_e32 v65, v66, v65
	v_div_scale_f32 v66, vcc, 1.0, v63, 1.0
	v_mul_f32_e32 v67, v66, v65
	v_fma_f32 v68, -v64, v67, v66
	v_fmac_f32_e32 v67, v68, v65
	v_fma_f32 v64, -v64, v67, v66
	v_div_fmas_f32 v64, v64, v65, v67
	v_div_fixup_f32 v63, v64, v63, 1.0
	v_mul_f32_e32 v64, v5, v59
	v_mul_f32_e32 v65, v64, v64
	v_sub_f32_e32 v61, 1.0, v61
	s_nop 0
	v_mov_b32_dpp v65, v65 quad_perm:[1,0,3,2] row_mask:0xf bank_mask:0xf bound_ctrl:1
	v_fmac_f32_e32 v65, v64, v64
	s_nop 1
	v_add_f32_dpp v65, v65, v65 quad_perm:[2,3,0,1] row_mask:0xf bank_mask:0xf bound_ctrl:1
	s_nop 1
	v_add_f32_dpp v65, v65, v65 row_half_mirror row_mask:0xf bank_mask:0xf bound_ctrl:1
	s_nop 1
	v_add_f32_dpp v65, v65, v65 row_mirror row_mask:0xf bank_mask:0xf bound_ctrl:1
	s_nop 0
	v_readlane_b32 s13, v65, 16
	v_readlane_b32 s12, v65, 0
	s_nop 0
	v_mov_b32_e32 v66, s13
	v_readlane_b32 s13, v65, 48
	v_add_f32_e32 v66, s12, v66
	v_readlane_b32 s12, v65, 32
	v_mov_b32_e32 v65, s13
	s_nop 0
	v_add_f32_e32 v65, s12, v65
	v_add_f32_e32 v65, v66, v65
	v_max_f32_e32 v65, 0x179abe15, v65
	v_rsq_f32_e32 v65, v65
	s_nop 0
	v_mul_f32_e32 v64, v64, v65
	v_add_f32_e32 v65, -1.0, v63
	v_mul_f32_e32 v63, v63, v64
	v_cvt_pk_bf16_f32 v58, -v64, s0
	v_fma_f32 v65, v3, v65, 1.0
	ds_write_b16 v109, v58 offset:41472
	v_cvt_pk_bf16_f32 v58, v63, s0
	v_mul_f32_e32 v59, v59, v65
	ds_write_b16 v109, v58 offset:49664
	v_cvt_pk_bf16_f32 v58, v60, s0
	v_mov_b32_e32 v60, v49
	v_cvt_pk_bf16_f32 v59, v59, s0
	ds_write_b16 v109, v58 offset:57856
	v_cvt_pk_bf16_f32 v58, v61, s0
	v_fmac_f32_e32 v60, v51, v23
	v_mov_b32_e32 v51, v48
	ds_write_b16 v109, v59 offset:25088
	ds_write_b16 v108, v58 offset:53760
	v_pk_add_f32 v[58:59], v[40:41], v[48:49] neg_lo:[0,1] neg_hi:[0,1]
	v_fmac_f32_e32 v51, v50, v19
	v_sub_f32_e32 v50, v120, v119
	v_fmac_f32_e32 v51, v58, v114
	v_fma_f32 v50, v50, v1, v119
	v_sub_f32_e32 v58, v118, v119
	v_fmac_f32_e32 v50, v58, v21
	v_div_scale_f32 v58, s[12:13], v56, v56, s39
	v_fmac_f32_e32 v60, v59, v115
	v_rcp_f32_e32 v59, v58
	v_cvt_pk_bf16_f32 v50, v50, s0
	ds_write_b16 v109, v50 offset:33792
	v_pk_add_f32 v[48:49], v[48:49], v[40:41] neg_lo:[0,1] neg_hi:[0,1]
	v_fma_f32 v61, -v58, v59, 1.0
	v_fmac_f32_e32 v59, v61, v59
	v_div_scale_f32 v61, vcc, s39, v56, s39
	v_mul_f32_e32 v62, v61, v59
	v_fma_f32 v63, -v58, v62, v61
	v_fmac_f32_e32 v62, v63, v59
	v_fma_f32 v58, -v58, v62, v61
	v_div_fmas_f32 v58, v58, v59, v62
	v_div_fixup_f32 v56, v58, v56, s39
	v_div_scale_f32 v58, s[12:13], v54, v54, s39
	v_rcp_f32_e32 v59, v58
	v_mul_f32_e32 v56, 0x3fb8aa3b, v56
	v_exp_f32_e32 v56, v56
	v_fma_f32 v61, -v58, v59, 1.0
	v_fmac_f32_e32 v59, v61, v59
	v_div_scale_f32 v61, vcc, s39, v54, s39
	v_mul_f32_e32 v62, v61, v59
	v_fma_f32 v63, -v58, v62, v61
	v_fmac_f32_e32 v62, v63, v59
	v_fma_f32 v58, -v58, v62, v61
	v_div_fmas_f32 v58, v58, v59, v62
	v_div_fixup_f32 v54, v58, v54, s39
	v_div_scale_f32 v58, s[12:13], v52, v52, 1.0
	v_rcp_f32_e32 v59, v58
	v_mul_f32_e32 v54, 0x3fb8aa3b, v54
	v_exp_f32_e32 v54, v54
	v_sub_f32_e32 v56, 1.0, v56
	v_fma_f32 v61, -v58, v59, 1.0
	v_fmac_f32_e32 v59, v61, v59
	v_div_scale_f32 v61, vcc, 1.0, v52, 1.0
	v_mul_f32_e32 v62, v61, v59
	v_fma_f32 v63, -v58, v62, v61
	v_fmac_f32_e32 v62, v63, v59
	v_fma_f32 v58, -v58, v62, v61
	v_div_fmas_f32 v58, v58, v59, v62
	v_div_fixup_f32 v52, v58, v52, 1.0
	v_mul_f32_e32 v58, v5, v51
	v_mul_f32_e32 v59, v58, v58
	v_sub_f32_e32 v54, 1.0, v54
	s_nop 0
	v_mov_b32_dpp v59, v59 quad_perm:[1,0,3,2] row_mask:0xf bank_mask:0xf bound_ctrl:1
	v_fmac_f32_e32 v59, v58, v58
	s_nop 1
	v_add_f32_dpp v59, v59, v59 quad_perm:[2,3,0,1] row_mask:0xf bank_mask:0xf bound_ctrl:1
	s_nop 1
	v_add_f32_dpp v59, v59, v59 row_half_mirror row_mask:0xf bank_mask:0xf bound_ctrl:1
	s_nop 1
	v_add_f32_dpp v59, v59, v59 row_mirror row_mask:0xf bank_mask:0xf bound_ctrl:1
	s_nop 0
	v_readlane_b32 s13, v59, 16
	v_readlane_b32 s12, v59, 0
	s_nop 0
	v_mov_b32_e32 v61, s13
	v_readlane_b32 s13, v59, 48
	v_add_f32_e32 v61, s12, v61
	v_readlane_b32 s12, v59, 32
	v_mov_b32_e32 v59, s13
	s_nop 0
	v_add_f32_e32 v59, s12, v59
	v_add_f32_e32 v59, v61, v59
	v_max_f32_e32 v59, 0x179abe15, v59
	v_rsq_f32_e32 v59, v59
	s_nop 0
	v_mul_f32_e32 v58, v58, v59
	v_add_f32_e32 v59, -1.0, v52
	v_mul_f32_e32 v52, v52, v58
	v_cvt_pk_bf16_f32 v50, -v58, s0
	v_fma_f32 v59, v3, v59, 1.0
	ds_write_b16 v109, v50 offset:41984
	v_cvt_pk_bf16_f32 v50, v52, s0
	v_mul_f32_e32 v51, v51, v59
	ds_write_b16 v109, v50 offset:50176
	v_cvt_pk_bf16_f32 v50, v56, s0
	v_mov_b32_e32 v52, v41
	v_cvt_pk_bf16_f32 v51, v51, s0
	ds_write_b16 v109, v50 offset:58368
	v_cvt_pk_bf16_f32 v50, v54, s0
	v_fmac_f32_e32 v52, v49, v23
	v_mov_b32_e32 v49, v40
	ds_write_b16 v109, v51 offset:25600
	ds_write_b16 v108, v50 offset:54272
	v_pk_add_f32 v[50:51], v[38:39], v[40:41] neg_lo:[0,1] neg_hi:[0,1]
	v_fmac_f32_e32 v49, v48, v19
	v_sub_f32_e32 v48, v119, v118
	v_fmac_f32_e32 v49, v50, v114
	v_fma_f32 v48, v48, v1, v118
	v_sub_f32_e32 v50, v117, v118
	v_fmac_f32_e32 v48, v50, v21
	v_add_f32_e32 v50, v11, v57
	v_mul_f32_e32 v50, 0xbfb8aa3b, v50
	v_exp_f32_e32 v50, v50
	v_fmac_f32_e32 v52, v51, v115
	v_cvt_pk_bf16_f32 v48, v48, s0
	ds_write_b16 v109, v48 offset:34304
	v_add_f32_e32 v50, 1.0, v50
	v_div_scale_f32 v51, s[12:13], v50, v50, s39
	v_rcp_f32_e32 v54, v51
	v_pk_add_f32 v[40:41], v[40:41], v[38:39] neg_lo:[0,1] neg_hi:[0,1]
	v_cvt_pk_bf16_f32 v52, v52, s0
	ds_write_b16 v109, v52 offset:17920
	v_fma_f32 v56, -v51, v54, 1.0
	v_fmac_f32_e32 v54, v56, v54
	v_div_scale_f32 v56, vcc, s39, v50, s39
	v_mul_f32_e32 v57, v56, v54
	v_fma_f32 v58, -v51, v57, v56
	v_fmac_f32_e32 v57, v58, v54
	v_fma_f32 v51, -v51, v57, v56
	v_div_fmas_f32 v51, v51, v54, v57
	v_div_fixup_f32 v50, v51, v50, s39
	v_add_f32_e32 v51, v9, v55
	v_mul_f32_e32 v51, 0xbfb8aa3b, v51
	v_exp_f32_e32 v51, v51
	v_mul_f32_e32 v50, 0x3fb8aa3b, v50
	v_exp_f32_e32 v50, v50
	v_cvt_pk_bf16_f32 v59, v60, s0
	v_add_f32_e32 v51, 1.0, v51
	v_div_scale_f32 v54, s[12:13], v51, v51, s39
	v_rcp_f32_e32 v55, v54
	v_sub_f32_e32 v50, 1.0, v50
	ds_write_b16 v109, v59 offset:17408
	v_fma_f32 v56, -v54, v55, 1.0
	v_fmac_f32_e32 v55, v56, v55
	v_div_scale_f32 v56, vcc, s39, v51, s39
	v_mul_f32_e32 v57, v56, v55
	v_fma_f32 v58, -v54, v57, v56
	v_fmac_f32_e32 v57, v58, v55
	v_fma_f32 v54, -v54, v57, v56
	v_div_fmas_f32 v54, v54, v55, v57
	v_div_fixup_f32 v51, v54, v51, s39
	v_div_scale_f32 v54, s[12:13], v53, v53, 1.0
	v_rcp_f32_e32 v55, v54
	v_mul_f32_e32 v51, 0x3fb8aa3b, v51
	v_exp_f32_e32 v51, v51
	v_fma_f32 v56, -v54, v55, 1.0
	v_fmac_f32_e32 v55, v56, v55
	v_div_scale_f32 v56, vcc, 1.0, v53, 1.0
	v_mul_f32_e32 v57, v56, v55
	v_fma_f32 v58, -v54, v57, v56
	v_fmac_f32_e32 v57, v58, v55
	v_fma_f32 v54, -v54, v57, v56
	v_div_fmas_f32 v54, v54, v55, v57
	v_div_fixup_f32 v53, v54, v53, 1.0
	v_mul_f32_e32 v54, v5, v49
	v_mul_f32_e32 v55, v54, v54
	v_sub_f32_e32 v51, 1.0, v51
	s_nop 0
	v_mov_b32_dpp v55, v55 quad_perm:[1,0,3,2] row_mask:0xf bank_mask:0xf bound_ctrl:1
	v_fmac_f32_e32 v55, v54, v54
	s_nop 1
	v_add_f32_dpp v55, v55, v55 quad_perm:[2,3,0,1] row_mask:0xf bank_mask:0xf bound_ctrl:1
	s_nop 1
	v_add_f32_dpp v55, v55, v55 row_half_mirror row_mask:0xf bank_mask:0xf bound_ctrl:1
	s_nop 1
	v_add_f32_dpp v55, v55, v55 row_mirror row_mask:0xf bank_mask:0xf bound_ctrl:1
	s_nop 0
	v_readlane_b32 s13, v55, 16
	v_readlane_b32 s12, v55, 0
	s_nop 0
	v_mov_b32_e32 v56, s13
	v_readlane_b32 s13, v55, 48
	v_add_f32_e32 v56, s12, v56
	v_readlane_b32 s12, v55, 32
	v_mov_b32_e32 v55, s13
	s_nop 0
	v_add_f32_e32 v55, s12, v55
	v_add_f32_e32 v55, v56, v55
	v_max_f32_e32 v55, 0x179abe15, v55
	v_rsq_f32_e32 v55, v55
	s_nop 0
	v_mul_f32_e32 v54, v54, v55
	v_add_f32_e32 v55, -1.0, v53
	v_mul_f32_e32 v53, v53, v54
	v_cvt_pk_bf16_f32 v48, -v54, s0
	v_fma_f32 v55, v3, v55, 1.0
	ds_write_b16 v109, v48 offset:42496
	v_cvt_pk_bf16_f32 v48, v53, s0
	v_mul_f32_e32 v49, v49, v55
	ds_write_b16 v109, v48 offset:50688
	v_cvt_pk_bf16_f32 v48, v50, s0
	v_mov_b32_e32 v50, v39
	v_cvt_pk_bf16_f32 v49, v49, s0
	ds_write_b16 v109, v48 offset:58880
	v_cvt_pk_bf16_f32 v48, v51, s0
	v_fmac_f32_e32 v50, v41, v23
	v_mov_b32_e32 v41, v38
	ds_write_b16 v109, v49 offset:26112
	ds_write_b16 v108, v48 offset:54784
	v_pk_add_f32 v[48:49], v[32:33], v[38:39] neg_lo:[0,1] neg_hi:[0,1]
	v_fmac_f32_e32 v41, v40, v19
	v_sub_f32_e32 v40, v118, v117
	v_fmac_f32_e32 v41, v48, v114
	v_fma_f32 v40, v40, v1, v117
	v_sub_f32_e32 v48, v116, v117
	v_fmac_f32_e32 v40, v48, v21
	v_div_scale_f32 v48, s[12:13], v46, v46, s39
	v_fmac_f32_e32 v50, v49, v115
	v_rcp_f32_e32 v49, v48
	v_cvt_pk_bf16_f32 v40, v40, s0
	ds_write_b16 v109, v40 offset:34816
	v_pk_add_f32 v[38:39], v[38:39], v[32:33] neg_lo:[0,1] neg_hi:[0,1]
	v_fma_f32 v51, -v48, v49, 1.0
	v_fmac_f32_e32 v49, v51, v49
	v_div_scale_f32 v51, vcc, s39, v46, s39
	v_mul_f32_e32 v52, v51, v49
	v_fma_f32 v53, -v48, v52, v51
	v_fmac_f32_e32 v52, v53, v49
	v_fma_f32 v48, -v48, v52, v51
	v_div_fmas_f32 v48, v48, v49, v52
	v_div_fixup_f32 v46, v48, v46, s39
	v_div_scale_f32 v48, s[12:13], v44, v44, s39
	v_rcp_f32_e32 v49, v48
	v_mul_f32_e32 v46, 0x3fb8aa3b, v46
	v_exp_f32_e32 v46, v46
	v_fma_f32 v51, -v48, v49, 1.0
	v_fmac_f32_e32 v49, v51, v49
	v_div_scale_f32 v51, vcc, s39, v44, s39
	v_mul_f32_e32 v52, v51, v49
	v_fma_f32 v53, -v48, v52, v51
	v_fmac_f32_e32 v52, v53, v49
	v_fma_f32 v48, -v48, v52, v51
	v_div_fmas_f32 v48, v48, v49, v52
	v_div_fixup_f32 v44, v48, v44, s39
	v_div_scale_f32 v48, s[12:13], v42, v42, 1.0
	v_rcp_f32_e32 v49, v48
	v_mul_f32_e32 v44, 0x3fb8aa3b, v44
	v_exp_f32_e32 v44, v44
	v_sub_f32_e32 v46, 1.0, v46
	v_fma_f32 v51, -v48, v49, 1.0
	v_fmac_f32_e32 v49, v51, v49
	v_div_scale_f32 v51, vcc, 1.0, v42, 1.0
	v_mul_f32_e32 v52, v51, v49
	v_fma_f32 v53, -v48, v52, v51
	v_fmac_f32_e32 v52, v53, v49
	v_fma_f32 v48, -v48, v52, v51
	v_div_fmas_f32 v48, v48, v49, v52
	v_div_fixup_f32 v42, v48, v42, 1.0
	v_mul_f32_e32 v48, v5, v41
	v_mul_f32_e32 v49, v48, v48
	v_sub_f32_e32 v44, 1.0, v44
	s_nop 0
	v_mov_b32_dpp v49, v49 quad_perm:[1,0,3,2] row_mask:0xf bank_mask:0xf bound_ctrl:1
	v_fmac_f32_e32 v49, v48, v48
	s_nop 1
	v_add_f32_dpp v49, v49, v49 quad_perm:[2,3,0,1] row_mask:0xf bank_mask:0xf bound_ctrl:1
	s_nop 1
	v_add_f32_dpp v49, v49, v49 row_half_mirror row_mask:0xf bank_mask:0xf bound_ctrl:1
	s_nop 1
	v_add_f32_dpp v49, v49, v49 row_mirror row_mask:0xf bank_mask:0xf bound_ctrl:1
	s_nop 0
	v_readlane_b32 s13, v49, 16
	v_readlane_b32 s12, v49, 0
	s_nop 0
	v_mov_b32_e32 v51, s13
	v_readlane_b32 s13, v49, 48
	v_add_f32_e32 v51, s12, v51
	v_readlane_b32 s12, v49, 32
	v_mov_b32_e32 v49, s13
	s_nop 0
	v_add_f32_e32 v49, s12, v49
	v_add_f32_e32 v49, v51, v49
	v_max_f32_e32 v49, 0x179abe15, v49
	v_rsq_f32_e32 v49, v49
	s_nop 0
	v_mul_f32_e32 v48, v48, v49
	v_add_f32_e32 v49, -1.0, v42
	v_mul_f32_e32 v42, v42, v48
	v_cvt_pk_bf16_f32 v40, -v48, s0
	v_fma_f32 v49, v3, v49, 1.0
	ds_write_b16 v109, v40 offset:43008
	v_cvt_pk_bf16_f32 v40, v42, s0
	v_mul_f32_e32 v41, v41, v49
	ds_write_b16 v109, v40 offset:51200
	v_cvt_pk_bf16_f32 v40, v46, s0
	v_mov_b32_e32 v42, v33
	v_cvt_pk_bf16_f32 v41, v41, s0
	ds_write_b16 v109, v40 offset:59392
	v_cvt_pk_bf16_f32 v40, v44, s0
	v_fmac_f32_e32 v42, v39, v23
	v_mov_b32_e32 v39, v32
	ds_write_b16 v109, v41 offset:26624
	ds_write_b16 v108, v40 offset:55296
	v_pk_add_f32 v[40:41], v[26:27], v[32:33] neg_lo:[0,1] neg_hi:[0,1]
	v_fmac_f32_e32 v39, v38, v19
	v_sub_f32_e32 v38, v117, v116
	v_fmac_f32_e32 v39, v40, v114
	v_fma_f32 v38, v38, v1, v116
	v_sub_f32_e32 v40, v15, v116
	v_fmac_f32_e32 v38, v40, v21
	v_add_f32_e32 v40, v11, v47
	v_mul_f32_e32 v40, 0xbfb8aa3b, v40
	v_exp_f32_e32 v40, v40
	v_fmac_f32_e32 v42, v41, v115
	v_cvt_pk_bf16_f32 v38, v38, s0
	ds_write_b16 v109, v38 offset:35328
	v_add_f32_e32 v40, 1.0, v40
	v_div_scale_f32 v41, s[12:13], v40, v40, s39
	v_rcp_f32_e32 v44, v41
	v_pk_add_f32 v[32:33], v[32:33], v[26:27] neg_lo:[0,1] neg_hi:[0,1]
	v_cvt_pk_bf16_f32 v42, v42, s0
	ds_write_b16 v109, v42 offset:18944
	v_fma_f32 v46, -v41, v44, 1.0
	v_fmac_f32_e32 v44, v46, v44
	v_div_scale_f32 v46, vcc, s39, v40, s39
	v_mul_f32_e32 v47, v46, v44
	v_fma_f32 v48, -v41, v47, v46
	v_fmac_f32_e32 v47, v48, v44
	v_fma_f32 v41, -v41, v47, v46
	v_div_fmas_f32 v41, v41, v44, v47
	v_div_fixup_f32 v40, v41, v40, s39
	v_add_f32_e32 v41, v9, v45
	v_mul_f32_e32 v41, 0xbfb8aa3b, v41
	v_exp_f32_e32 v41, v41
	v_mul_f32_e32 v40, 0x3fb8aa3b, v40
	v_exp_f32_e32 v40, v40
	v_add_f32_e32 v9, v9, v35
	v_add_f32_e32 v41, 1.0, v41
	v_div_scale_f32 v44, s[12:13], v41, v41, s39
	v_rcp_f32_e32 v45, v44
	v_sub_f32_e32 v40, 1.0, v40
	v_mul_f32_e32 v9, 0xbfb8aa3b, v9
	v_exp_f32_e32 v9, v9
	v_fma_f32 v46, -v44, v45, 1.0
	v_fmac_f32_e32 v45, v46, v45
	v_div_scale_f32 v46, vcc, s39, v41, s39
	v_mul_f32_e32 v47, v46, v45
	v_fma_f32 v48, -v44, v47, v46
	v_fmac_f32_e32 v47, v48, v45
	v_fma_f32 v44, -v44, v47, v46
	v_div_fmas_f32 v44, v44, v45, v47
	v_div_fixup_f32 v41, v44, v41, s39
	v_div_scale_f32 v44, s[12:13], v43, v43, 1.0
	v_rcp_f32_e32 v45, v44
	v_mul_f32_e32 v41, 0x3fb8aa3b, v41
	v_exp_f32_e32 v41, v41
	v_add_f32_e32 v9, 1.0, v9
	v_fma_f32 v46, -v44, v45, 1.0
	v_fmac_f32_e32 v45, v46, v45
	v_div_scale_f32 v46, vcc, 1.0, v43, 1.0
	v_mul_f32_e32 v47, v46, v45
	v_fma_f32 v48, -v44, v47, v46
	v_fmac_f32_e32 v47, v48, v45
	v_fma_f32 v44, -v44, v47, v46
	v_div_fmas_f32 v44, v44, v45, v47
	v_div_fixup_f32 v43, v44, v43, 1.0
	v_mul_f32_e32 v44, v5, v39
	v_mul_f32_e32 v45, v44, v44
	v_sub_f32_e32 v41, 1.0, v41
	v_cvt_pk_bf16_f32 v49, v50, s0
	v_mov_b32_dpp v45, v45 quad_perm:[1,0,3,2] row_mask:0xf bank_mask:0xf bound_ctrl:1
	v_fmac_f32_e32 v45, v44, v44
	ds_write_b16 v109, v49 offset:18432
	s_nop 0
	v_add_f32_dpp v45, v45, v45 quad_perm:[2,3,0,1] row_mask:0xf bank_mask:0xf bound_ctrl:1
	s_nop 1
	v_add_f32_dpp v45, v45, v45 row_half_mirror row_mask:0xf bank_mask:0xf bound_ctrl:1
	s_nop 1
	v_add_f32_dpp v45, v45, v45 row_mirror row_mask:0xf bank_mask:0xf bound_ctrl:1
	s_nop 0
	v_readlane_b32 s13, v45, 16
	v_readlane_b32 s12, v45, 0
	s_nop 0
	v_mov_b32_e32 v46, s13
	v_readlane_b32 s13, v45, 48
	v_add_f32_e32 v46, s12, v46
	v_readlane_b32 s12, v45, 32
	v_mov_b32_e32 v45, s13
	s_nop 0
	v_add_f32_e32 v45, s12, v45
	v_add_f32_e32 v45, v46, v45
	v_max_f32_e32 v45, 0x179abe15, v45
	v_rsq_f32_e32 v45, v45
	s_nop 0
	v_mul_f32_e32 v44, v44, v45
	v_add_f32_e32 v45, -1.0, v43
	v_mul_f32_e32 v43, v43, v44
	v_cvt_pk_bf16_f32 v38, -v44, s0
	v_fma_f32 v45, v3, v45, 1.0
	ds_write_b16 v109, v38 offset:43520
	v_cvt_pk_bf16_f32 v38, v43, s0
	v_mul_f32_e32 v39, v39, v45
	ds_write_b16 v109, v38 offset:51712
	v_cvt_pk_bf16_f32 v38, v40, s0
	v_mov_b32_e32 v40, v27
	v_cvt_pk_bf16_f32 v39, v39, s0
	ds_write_b16 v109, v38 offset:59904
	v_cvt_pk_bf16_f32 v38, v41, s0
	v_fmac_f32_e32 v40, v33, v23
	v_mov_b32_e32 v33, v26
	ds_write_b16 v109, v39 offset:27136
	ds_write_b16 v108, v38 offset:55808
	v_pk_add_f32 v[38:39], v[24:25], v[26:27] neg_lo:[0,1] neg_hi:[0,1]
	v_fmac_f32_e32 v33, v32, v19
	v_sub_f32_e32 v32, v116, v15
	v_fmac_f32_e32 v33, v38, v114
	v_fma_f32 v32, v32, v1, v15
	v_sub_f32_e32 v38, v13, v15
	v_fmac_f32_e32 v32, v38, v21
	v_div_scale_f32 v38, s[12:13], v36, v36, s39
	v_fmac_f32_e32 v40, v39, v115
	v_rcp_f32_e32 v39, v38
	v_sub_f32_e32 v15, v15, v13
	v_fmac_f32_e32 v13, v15, v1
	v_add_f32_e32 v1, v11, v37
	v_fma_f32 v41, -v38, v39, 1.0
	v_fmac_f32_e32 v39, v41, v39
	v_div_scale_f32 v41, vcc, s39, v36, s39
	v_mul_f32_e32 v42, v41, v39
	v_fma_f32 v43, -v38, v42, v41
	v_fmac_f32_e32 v42, v43, v39
	v_fma_f32 v38, -v38, v42, v41
	v_div_fmas_f32 v38, v38, v39, v42
	v_div_fixup_f32 v36, v38, v36, s39
	v_div_scale_f32 v38, s[12:13], v34, v34, s39
	v_rcp_f32_e32 v39, v38
	v_mul_f32_e32 v1, 0xbfb8aa3b, v1
	v_exp_f32_e32 v1, v1
	v_fmac_f32_e32 v13, v17, v21
	v_fma_f32 v41, -v38, v39, 1.0
	v_fmac_f32_e32 v39, v41, v39
	v_div_scale_f32 v41, vcc, s39, v34, s39
	v_mul_f32_e32 v42, v41, v39
	v_fma_f32 v43, -v38, v42, v41
	v_fmac_f32_e32 v42, v43, v39
	v_fma_f32 v38, -v38, v42, v41
	v_div_fmas_f32 v38, v38, v39, v42
	v_div_fixup_f32 v34, v38, v34, s39
	v_div_scale_f32 v38, s[12:13], v30, v30, 1.0
	v_rcp_f32_e32 v39, v38
	v_add_f32_e32 v1, 1.0, v1
	v_pk_add_f32 v[26:27], v[26:27], v[24:25] neg_lo:[0,1] neg_hi:[0,1]
	v_mul_f32_e32 v36, 0x3fb8aa3b, v36
	v_fma_f32 v41, -v38, v39, 1.0
	v_fmac_f32_e32 v39, v41, v39
	v_div_scale_f32 v41, vcc, 1.0, v30, 1.0
	v_mul_f32_e32 v42, v41, v39
	v_fma_f32 v43, -v38, v42, v41
	v_fmac_f32_e32 v42, v43, v39
	v_fma_f32 v38, -v38, v42, v41
	v_div_fmas_f32 v38, v38, v39, v42
	v_div_fixup_f32 v30, v38, v30, 1.0
	v_mul_f32_e32 v38, v5, v33
	v_mul_f32_e32 v39, v38, v38
	v_fmac_f32_e32 v24, v26, v19
	v_fmac_f32_e32 v24, v28, v114
	v_mov_b32_dpp v39, v39 quad_perm:[1,0,3,2] row_mask:0xf bank_mask:0xf bound_ctrl:1
	v_fmac_f32_e32 v39, v38, v38
	v_mul_f32_e32 v5, v5, v24
	v_exp_f32_e32 v36, v36
	v_add_f32_dpp v39, v39, v39 quad_perm:[2,3,0,1] row_mask:0xf bank_mask:0xf bound_ctrl:1
	v_mul_f32_e32 v34, 0x3fb8aa3b, v34
	v_exp_f32_e32 v34, v34
	v_add_f32_dpp v39, v39, v39 row_half_mirror row_mask:0xf bank_mask:0xf bound_ctrl:1
	v_sub_f32_e32 v36, 1.0, v36
	v_cvt_pk_bf16_f32 v32, v32, s0
	v_add_f32_dpp v39, v39, v39 row_mirror row_mask:0xf bank_mask:0xf bound_ctrl:1
	v_sub_f32_e32 v34, 1.0, v34
	v_readlane_b32 s13, v39, 16
	v_readlane_b32 s12, v39, 0
	ds_write_b16 v109, v32 offset:35840
	v_mov_b32_e32 v41, s13
	v_readlane_b32 s13, v39, 48
	v_add_f32_e32 v41, s12, v41
	v_readlane_b32 s12, v39, 32
	v_mov_b32_e32 v39, s13
	s_nop 0
	v_add_f32_e32 v39, s12, v39
	v_div_scale_f32 v11, s[12:13], v1, v1, s39
	v_rcp_f32_e32 v15, v11
	v_add_f32_e32 v39, v41, v39
	v_max_f32_e32 v39, 0x179abe15, v39
	v_rsq_f32_e32 v39, v39
	v_fma_f32 v17, -v11, v15, 1.0
	v_fmac_f32_e32 v15, v17, v15
	v_div_scale_f32 v17, vcc, s39, v1, s39
	v_mul_f32_e32 v19, v17, v15
	v_fma_f32 v21, -v11, v19, v17
	v_fmac_f32_e32 v19, v21, v15
	v_fma_f32 v11, -v11, v19, v17
	v_div_fmas_f32 v11, v11, v15, v19
	v_div_fixup_f32 v1, v11, v1, s39
	v_div_scale_f32 v11, s[12:13], v9, v9, s39
	v_rcp_f32_e32 v15, v11
	v_mul_f32_e32 v38, v38, v39
	v_mul_f32_e32 v1, 0x3fb8aa3b, v1
	v_add_f32_e32 v39, -1.0, v30
	v_fma_f32 v17, -v11, v15, 1.0
	v_fmac_f32_e32 v15, v17, v15
	v_div_scale_f32 v17, vcc, s39, v9, s39
	v_mul_f32_e32 v19, v17, v15
	v_fma_f32 v21, -v11, v19, v17
	v_fmac_f32_e32 v19, v21, v15
	v_fma_f32 v11, -v11, v19, v17
	v_div_fmas_f32 v11, v11, v15, v19
	v_div_fixup_f32 v9, v11, v9, s39
	v_div_scale_f32 v11, s[12:13], v7, v7, 1.0
	v_rcp_f32_e32 v15, v11
	v_mul_f32_e32 v30, v30, v38
	v_exp_f32_e32 v1, v1
	v_mul_f32_e32 v9, 0x3fb8aa3b, v9
	v_fma_f32 v17, -v11, v15, 1.0
	v_fmac_f32_e32 v15, v17, v15
	v_div_scale_f32 v17, vcc, 1.0, v7, 1.0
	v_mul_f32_e32 v19, v17, v15
	v_fma_f32 v21, -v11, v19, v17
	v_fmac_f32_e32 v19, v21, v15
	v_fma_f32 v11, -v11, v19, v17
	v_div_fmas_f32 v11, v11, v15, v19
	v_div_fixup_f32 v7, v11, v7, 1.0
	v_mul_f32_e32 v11, v5, v5
	v_fma_f32 v39, v3, v39, 1.0
	v_cvt_pk_bf16_f32 v30, v30, s0
	v_mov_b32_dpp v11, v11 quad_perm:[1,0,3,2] row_mask:0xf bank_mask:0xf bound_ctrl:1
	v_fmac_f32_e32 v11, v5, v5
	v_exp_f32_e32 v9, v9
	ds_write_b16 v109, v30 offset:52224
	v_add_f32_dpp v11, v11, v11 quad_perm:[2,3,0,1] row_mask:0xf bank_mask:0xf bound_ctrl:1
	v_cvt_pk_bf16_f32 v30, v36, s0
	ds_write_b16 v109, v30 offset:60416
	v_add_f32_dpp v11, v11, v11 row_half_mirror row_mask:0xf bank_mask:0xf bound_ctrl:1
	v_cvt_pk_bf16_f32 v30, v34, s0
	ds_write_b16 v108, v30 offset:56320
	v_add_f32_dpp v11, v11, v11 row_mirror row_mask:0xf bank_mask:0xf bound_ctrl:1
	v_mov_b32_e32 v30, v25
	v_readlane_b32 s13, v11, 16
	v_readlane_b32 s12, v11, 0
	v_sub_f32_e32 v1, 1.0, v1
	v_mov_b32_e32 v15, s13
	v_readlane_b32 s13, v11, 48
	v_add_f32_e32 v15, s12, v15
	v_readlane_b32 s12, v11, 32
	v_mov_b32_e32 v11, s13
	v_fmac_f32_e32 v30, v27, v23
	v_add_f32_e32 v11, s12, v11
	v_add_f32_e32 v11, v15, v11
	v_max_f32_e32 v11, 0x179abe15, v11
	v_rsq_f32_e32 v11, v11
	v_sub_f32_e32 v9, 1.0, v9
	v_cvt_pk_bf16_f32 v1, v1, s0
	v_fmac_f32_e32 v30, v29, v115
	v_mul_f32_e32 v5, v5, v11
	v_add_f32_e32 v11, -1.0, v7
	v_fma_f32 v3, v3, v11, 1.0
	v_mul_f32_e32 v3, v24, v3
	v_cvt_pk_bf16_f32 v3, v3, s0
	ds_write_b16 v109, v3 offset:28160
	v_cvt_pk_bf16_f32 v3, v13, s0
	v_mul_f32_e32 v7, v7, v5
	ds_write_b16 v109, v3 offset:36352
	v_cvt_pk_bf16_f32 v3, -v5, s0
	ds_write_b16 v109, v3 offset:44544
	v_cvt_pk_bf16_f32 v3, v7, s0
	ds_write_b16 v109, v1 offset:60928
	v_cvt_pk_bf16_f32 v1, v9, s0
	v_cvt_pk_bf16_f32 v11, v30, s0
	ds_write_b16 v109, v3 offset:52736
	ds_write_b16 v108, v1 offset:56832
	v_ashrrev_i32_e32 v1, 9, v0
	v_bfe_u32 v3, v0, 5, 4
	v_lshlrev_b32_e32 v7, 4, v0
	v_mul_f32_e32 v33, v33, v39
	ds_write_b16 v109, v11 offset:19968
	v_lshl_add_u32 v5, v1, 13, 16
	v_lshlrev_b32_e32 v11, 9, v3
	v_and_b32_e32 v176, 0x1f0, v7
	v_cvt_pk_bf16_f32 v39, v40, s0
	v_cvt_pk_bf16_f32 v33, v33, s0
	v_cvt_pk_bf16_f32 v32, -v38, s0
	v_add3_u32 v5, v5, v11, v176
	ds_write_b16 v109, v39 offset:19456
	ds_write_b16 v109, v33 offset:27648
	ds_write_b16 v109, v32 offset:44032
	s_waitcnt lgkmcnt(0)
	s_barrier
	ds_read_b128 v[24:27], v5 offset:12288
	v_or_b32_e32 v32, s20, v3
	v_mov_b64_e32 v[28:29], s[80:81]
	v_ashrrev_i32_e32 v33, 31, v32
	v_mad_i64_i32 v[30:31], s[12:13], v1, s40, v[28:29]
	v_lshlrev_b64 v[32:33], 9, v[32:33]
	v_ashrrev_i32_e32 v1, 9, v2
	v_bfe_u32 v5, v2, 5, 4
	v_lshl_add_u64 v[30:31], v[30:31], 0, v[32:33]
	v_lshl_add_u32 v2, v1, 13, 16
	v_lshlrev_b32_e32 v3, 9, v5
	v_lshl_add_u64 v[30:31], v[30:31], 0, v[176:177]
	v_add3_u32 v2, v2, v3, v176
	s_waitcnt lgkmcnt(0)
	global_store_dwordx4 v[30:31], v[24:27], off
	ds_read_b128 v[24:27], v2 offset:12288
	v_or_b32_e32 v30, s20, v5
	v_ashrrev_i32_e32 v31, 31, v30
	v_mad_i64_i32 v[2:3], s[12:13], v1, s40, v[28:29]
	v_lshlrev_b64 v[30:31], 9, v[30:31]
	v_lshl_add_u64 v[2:3], v[2:3], 0, v[30:31]
	v_lshl_add_u64 v[2:3], v[2:3], 0, v[176:177]
	v_ashrrev_i32_e32 v1, 9, v4
	s_waitcnt lgkmcnt(0)
	global_store_dwordx4 v[2:3], v[24:27], off
	v_lshl_add_u32 v2, v1, 13, 16
	v_add3_u32 v2, v2, v11, v176
	ds_read_b128 v[2:5], v2 offset:12288
	v_mad_i64_i32 v[24:25], s[12:13], v1, s40, v[28:29]
	v_lshl_add_u64 v[24:25], v[24:25], 0, v[32:33]
	v_lshl_add_u64 v[24:25], v[24:25], 0, v[176:177]
	v_ashrrev_i32_e32 v1, 9, v6
	v_bfe_u32 v9, v6, 5, 4
	s_waitcnt lgkmcnt(0)
	global_store_dwordx4 v[24:25], v[2:5], off
	v_or_b32_e32 v24, s20, v9
	v_ashrrev_i32_e32 v25, 31, v24
	v_lshl_add_u32 v2, v1, 13, 16
	v_lshlrev_b32_e32 v3, 9, v9
	v_add3_u32 v2, v2, v3, v176
	ds_read_b128 v[2:5], v2 offset:12288
	v_mad_i64_i32 v[6:7], s[12:13], v1, s40, v[28:29]
	v_lshlrev_b64 v[24:25], 9, v[24:25]
	v_lshl_add_u64 v[6:7], v[6:7], 0, v[24:25]
	v_lshl_add_u64 v[6:7], v[6:7], 0, v[176:177]
	v_ashrrev_i32_e32 v1, 9, v8
	s_waitcnt lgkmcnt(0)
	global_store_dwordx4 v[6:7], v[2:5], off
	v_mad_i64_i32 v[6:7], s[12:13], v1, s40, v[28:29]
	s_nop 0
	v_lshl_add_u32 v2, v1, 13, 16
	v_add3_u32 v2, v2, v11, v176
	ds_read_b128 v[2:5], v2 offset:12288
	v_lshl_add_u64 v[6:7], v[6:7], 0, v[32:33]
	v_lshl_add_u64 v[6:7], v[6:7], 0, v[176:177]
	v_ashrrev_i32_e32 v1, 9, v10
	v_bfe_u32 v8, v10, 5, 4
	s_waitcnt lgkmcnt(0)
	global_store_dwordx4 v[6:7], v[2:5], off
	v_mad_i64_i32 v[6:7], s[12:13], v1, s40, v[28:29]
	s_nop 0
	v_lshl_add_u32 v2, v1, 13, 16
	v_lshlrev_b32_e32 v3, 9, v8
	v_add3_u32 v2, v2, v3, v176
	ds_read_b128 v[2:5], v2 offset:12288
	v_or_b32_e32 v8, s20, v8
	v_ashrrev_i32_e32 v9, 31, v8
	v_lshlrev_b64 v[8:9], 9, v[8:9]
	v_lshl_add_u64 v[6:7], v[6:7], 0, v[8:9]
	v_lshl_add_u64 v[6:7], v[6:7], 0, v[176:177]
	v_ashrrev_i32_e32 v1, 9, v12
	s_waitcnt lgkmcnt(0)
	global_store_dwordx4 v[6:7], v[2:5], off
	v_mad_i64_i32 v[6:7], s[12:13], v1, s40, v[28:29]
	s_nop 0
	v_lshl_add_u32 v2, v1, 13, 16
	v_add3_u32 v2, v2, v11, v176
	ds_read_b128 v[2:5], v2 offset:12288
	v_lshl_add_u64 v[6:7], v[6:7], 0, v[32:33]
	v_lshl_add_u64 v[6:7], v[6:7], 0, v[176:177]
	v_ashrrev_i32_e32 v1, 9, v14
	v_bfe_u32 v8, v14, 5, 4
	s_waitcnt lgkmcnt(0)
	global_store_dwordx4 v[6:7], v[2:5], off
	v_mad_i64_i32 v[6:7], s[12:13], v1, s40, v[28:29]
	s_nop 0
	v_lshl_add_u32 v2, v1, 13, 16
	v_lshlrev_b32_e32 v3, 9, v8
	v_add3_u32 v2, v2, v3, v176
	ds_read_b128 v[2:5], v2 offset:12288
	v_or_b32_e32 v8, s20, v8
	v_ashrrev_i32_e32 v9, 31, v8
	v_lshlrev_b64 v[8:9], 9, v[8:9]
	v_lshl_add_u64 v[6:7], v[6:7], 0, v[8:9]
	v_lshl_add_u64 v[6:7], v[6:7], 0, v[176:177]
	v_ashrrev_i32_e32 v1, 9, v16
	s_waitcnt lgkmcnt(0)
	global_store_dwordx4 v[6:7], v[2:5], off
	v_mad_i64_i32 v[6:7], s[12:13], v1, s40, v[28:29]
	s_nop 0
	v_lshl_add_u32 v2, v1, 13, 16
	v_add3_u32 v2, v2, v11, v176
	ds_read_b128 v[2:5], v2 offset:12288
	v_lshl_add_u64 v[6:7], v[6:7], 0, v[32:33]
	v_lshl_add_u64 v[6:7], v[6:7], 0, v[176:177]
	v_ashrrev_i32_e32 v1, 9, v18
	v_bfe_u32 v8, v18, 5, 4
	s_waitcnt lgkmcnt(0)
	global_store_dwordx4 v[6:7], v[2:5], off
	v_mad_i64_i32 v[6:7], s[12:13], v1, s40, v[28:29]
	s_nop 0
	v_lshl_add_u32 v2, v1, 13, 16
	v_lshlrev_b32_e32 v3, 9, v8
	v_add3_u32 v2, v2, v3, v176
	ds_read_b128 v[2:5], v2 offset:12288
	v_or_b32_e32 v8, s20, v8
	v_ashrrev_i32_e32 v9, 31, v8
	v_lshlrev_b64 v[8:9], 9, v[8:9]
	v_lshl_add_u64 v[6:7], v[6:7], 0, v[8:9]
	v_lshl_add_u64 v[6:7], v[6:7], 0, v[176:177]
	v_ashrrev_i32_e32 v1, 9, v20
	s_waitcnt lgkmcnt(0)
	global_store_dwordx4 v[6:7], v[2:5], off
	v_mad_i64_i32 v[6:7], s[12:13], v1, s40, v[28:29]
	s_nop 0
	v_lshl_add_u32 v2, v1, 13, 16
	v_add3_u32 v2, v2, v11, v176
	ds_read_b128 v[2:5], v2 offset:12288
	v_lshl_add_u64 v[6:7], v[6:7], 0, v[32:33]
	v_lshl_add_u64 v[6:7], v[6:7], 0, v[176:177]
	v_ashrrev_i32_e32 v1, 9, v22
	v_bfe_u32 v8, v22, 5, 4
	s_waitcnt lgkmcnt(0)
	global_store_dwordx4 v[6:7], v[2:5], off
	v_mad_i64_i32 v[6:7], s[12:13], v1, s40, v[28:29]
	s_nop 0
	v_lshl_add_u32 v2, v1, 13, 16
	v_lshlrev_b32_e32 v3, 9, v8
	v_add3_u32 v2, v2, v3, v176
	ds_read_b128 v[2:5], v2 offset:12288
	v_or_b32_e32 v8, s20, v8
	v_ashrrev_i32_e32 v9, 31, v8
	v_lshlrev_b64 v[8:9], 9, v[8:9]
	v_lshl_add_u64 v[6:7], v[6:7], 0, v[8:9]
	v_add_u32_e32 v1, 0xc00, v0
	v_lshl_add_u64 v[6:7], v[6:7], 0, v[176:177]
	v_ashrrev_i32_e32 v1, 9, v1
	s_waitcnt lgkmcnt(0)
	global_store_dwordx4 v[6:7], v[2:5], off
	v_mad_i64_i32 v[6:7], s[12:13], v1, s40, v[28:29]
	s_nop 0
	v_lshl_add_u32 v2, v1, 13, 16
	v_add3_u32 v2, v2, v11, v176
	ds_read_b128 v[2:5], v2 offset:12288
	v_lshl_add_u64 v[6:7], v[6:7], 0, v[32:33]
	v_lshl_add_u64 v[6:7], v[6:7], 0, v[176:177]
	v_add_u32_e32 v0, 0xd00, v0
	s_waitcnt lgkmcnt(0)
	global_store_dwordx4 v[6:7], v[2:5], off
	v_bfe_u32 v6, v0, 5, 4
	s_nop 0
	v_ashrrev_i32_e32 v4, 9, v0
	v_lshl_add_u32 v0, v4, 13, 16
	v_lshlrev_b32_e32 v1, 9, v6
	v_add3_u32 v0, v0, v1, v176
	ds_read_b128 v[0:3], v0 offset:12288
	v_or_b32_e32 v6, s20, v6
	v_ashrrev_i32_e32 v7, 31, v6
	v_mad_i64_i32 v[4:5], s[12:13], v4, s40, v[28:29]
	v_lshlrev_b64 v[6:7], 9, v[6:7]
	v_lshl_add_u64 v[4:5], v[4:5], 0, v[6:7]
	v_lshl_add_u64 v[4:5], v[4:5], 0, v[176:177]
	s_waitcnt lgkmcnt(0)
	global_store_dwordx4 v[4:5], v[0:3], off
	s_barrier
	s_cbranch_scc0 .LBB0_177
